# compress item: W1 kept in MFMA-fragment order in the workspace (setup writes it that way), every weight-fragment load is one contiguous 1 KB access; swa loop ALiBi fold
# speedup vs baseline: 1.1518x; 1.0182x over previous
; __device__ __forceinline__ float bf2f(u16 b) { return __uint_as_float(((unsigned)b) << 16); }
; __device__ void item_compress(const Params& p, int layer, int kv, int b, int g, int ct, unsigned char* smem) {
;     ...
;   const u16* src = P_H + ((size_t)b * SEQ + (size_t)(cvalid ? 16 * c : 0)) * HS + col + quad * 8;
;   const u16* wb = w1t + (size_t)l15 * 2048 + quad * 8;
;   f32x4 acc[8];
; #pragma unroll
;   for (int j = 0; j < 8; ++j) acc[j] = f32x4{0.f, 0.f, 0.f, 0.f};
; #pragma unroll 4
;   for (int ii = 0; ii < 8; ++ii) {
;     const int i = wave * 8 + ii;
; #pragma unroll
;     for (int ks = 0; ks < 2; ++ks) {
;       uint4 raw = *(const uint4*)(src + (size_t)i * HS + ks * 32);
;       const float* pp = pe + i * 64 + ks * 32 + quad * 8;
;       float4 p0 = *(const float4*)pp, p1 = *(const float4*)(pp + 4);
;       bf16x8 a = pack8(bf2f((u16)(raw.x & 0xffff)) + p0.x, bf2f((u16)(raw.x >> 16)) + p0.y,
;                        bf2f((u16)(raw.y & 0xffff)) + p0.z, bf2f((u16)(raw.y >> 16)) + p0.w,
;                        bf2f((u16)(raw.z & 0xffff)) + p1.x, bf2f((u16)(raw.z >> 16)) + p1.y,
;                        bf2f((u16)(raw.w & 0xffff)) + p1.z, bf2f((u16)(raw.w >> 16)) + p1.w);
; #pragma unroll
;       for (int j = 0; j < 8; ++j) {
;         bf16x8 bfr = *(const bf16x8*)(wb + (size_t)(j * 16) * 2048 + i * 64 + ks * 32);
;         acc[j] = mfma16(a, bfr, acc[j]);
;       }
;     }
;   }
.LBB0_233:
	v_and_b32_e32 v52, 63, v73
	v_lshlrev_b32_e32 v52, 4, v52
	v_lshl_or_b32 v52, v75, 17, v52
	v_add_u32_e32 v54, 0x1000, v52
	s_add_u32 s38, s6, s86
	s_addc_u32 s39, s7, 0
	v_lshl_add_u64 v[68:69], v[48:49], 0, v[0:1]
	v_add_co_u32_e32 v68, vcc, 0x4924000, v68
	s_nop 1
	v_addc_co_u32_e32 v69, vcc, 0, v69, vcc
	v_mov_b32_e32 v70, v50
	v_mov_b32_e32 v71, v51
	global_load_dwordx4 v[80:83], v[68:69], off offset:1024
	global_load_dwordx4 v[84:87], v[70:71], off offset:0
	global_load_dwordx4 v[88:91], v[70:71], off offset:16
	global_load_dwordx4 v[92:95], v52, s[38:39] offset:0
	global_load_dwordx4 v[96:99], v52, s[38:39] offset:1024
	global_load_dwordx4 v[100:103], v52, s[38:39] offset:2048
	global_load_dwordx4 v[104:107], v52, s[38:39] offset:3072
	global_load_dwordx4 v[108:111], v54, s[38:39] offset:0
	global_load_dwordx4 v[112:115], v54, s[38:39] offset:1024
	global_load_dwordx4 v[116:119], v54, s[38:39] offset:2048
	global_load_dwordx4 v[120:123], v54, s[38:39] offset:3072
	s_add_u32 s38, s38, 0x2000
	s_addc_u32 s39, s39, 0
	global_load_dwordx4 v[124:127], v[68:69], off offset:1088
	global_load_dwordx4 v[128:131], v[70:71], off offset:128
	global_load_dwordx4 v[132:135], v[70:71], off offset:144
	global_load_dwordx4 v[136:139], v52, s[38:39] offset:0
	global_load_dwordx4 v[140:143], v52, s[38:39] offset:1024
	global_load_dwordx4 v[144:147], v52, s[38:39] offset:2048
	global_load_dwordx4 v[148:151], v52, s[38:39] offset:3072
	global_load_dwordx4 v[152:155], v54, s[38:39] offset:0
	global_load_dwordx4 v[156:159], v54, s[38:39] offset:1024
	global_load_dwordx4 v[160:163], v54, s[38:39] offset:2048
	global_load_dwordx4 v[164:167], v54, s[38:39] offset:3072
	s_add_u32 s38, s38, 0x2000
	s_addc_u32 s39, s39, 0
	v_add_co_u32_e32 v68, vcc, 0x1d00, v68
	s_nop 1
	v_addc_co_u32_e32 v69, vcc, 0, v69, vcc
	global_load_dwordx4 v[168:171], v[68:69], off offset:1024
	global_load_dwordx4 v[172:175], v[70:71], off offset:256
	global_load_dwordx4 v[176:179], v[70:71], off offset:272
	global_load_dwordx4 v[180:183], v52, s[38:39] offset:0
	global_load_dwordx4 v[184:187], v52, s[38:39] offset:1024
	global_load_dwordx4 v[188:191], v52, s[38:39] offset:2048
	global_load_dwordx4 v[192:195], v52, s[38:39] offset:3072
	global_load_dwordx4 v[196:199], v54, s[38:39] offset:0
	global_load_dwordx4 v[200:203], v54, s[38:39] offset:1024
	global_load_dwordx4 v[204:207], v54, s[38:39] offset:2048
	global_load_dwordx4 v[218:221], v54, s[38:39] offset:3072
	s_add_u32 s38, s38, 0x2000
	s_addc_u32 s39, s39, 0
	s_waitcnt vmcnt(22)
	v_lshlrev_b32_e32 v208, 16, v80
	v_and_b32_e32 v209, 0xffff0000, v80
	v_pk_add_f32 v[84:85], v[84:85], v[208:209]
	v_lshlrev_b32_e32 v208, 16, v81
	v_and_b32_e32 v209, 0xffff0000, v81
	v_pk_add_f32 v[86:87], v[86:87], v[208:209]
	v_lshlrev_b32_e32 v208, 16, v82
	v_and_b32_e32 v209, 0xffff0000, v82
	v_pk_add_f32 v[88:89], v[88:89], v[208:209]
	v_lshlrev_b32_e32 v208, 16, v83
	v_and_b32_e32 v209, 0xffff0000, v83
	v_pk_add_f32 v[90:91], v[90:91], v[208:209]
	v_cvt_pk_bf16_f32 v80, v84, v85
	v_cvt_pk_bf16_f32 v81, v86, v87
	v_cvt_pk_bf16_f32 v82, v88, v89
	v_cvt_pk_bf16_f32 v83, v90, v91
	s_nop 1
	v_mfma_f32_16x16x32_bf16 v[2:5], v[80:83], v[92:95], v[2:5]
	v_mfma_f32_16x16x32_bf16 v[30:33], v[80:83], v[96:99], v[30:33]
	v_mfma_f32_16x16x32_bf16 v[26:29], v[80:83], v[100:103], v[26:29]
	v_mfma_f32_16x16x32_bf16 v[22:25], v[80:83], v[104:107], v[22:25]
	v_mfma_f32_16x16x32_bf16 v[18:21], v[80:83], v[108:111], v[18:21]
	v_mfma_f32_16x16x32_bf16 v[14:17], v[80:83], v[112:115], v[14:17]
	v_mfma_f32_16x16x32_bf16 v[10:13], v[80:83], v[116:119], v[10:13]
	v_mfma_f32_16x16x32_bf16 v[6:9], v[80:83], v[120:123], v[6:9]
	global_load_dwordx4 v[80:83], v[68:69], off offset:1088
	global_load_dwordx4 v[84:87], v[70:71], off offset:384
	global_load_dwordx4 v[88:91], v[70:71], off offset:400
	global_load_dwordx4 v[92:95], v52, s[38:39] offset:0
	global_load_dwordx4 v[96:99], v52, s[38:39] offset:1024
	global_load_dwordx4 v[100:103], v52, s[38:39] offset:2048
	global_load_dwordx4 v[104:107], v52, s[38:39] offset:3072
	global_load_dwordx4 v[108:111], v54, s[38:39] offset:0
	global_load_dwordx4 v[112:115], v54, s[38:39] offset:1024
	global_load_dwordx4 v[116:119], v54, s[38:39] offset:2048
	global_load_dwordx4 v[120:123], v54, s[38:39] offset:3072
	s_add_u32 s38, s38, 0x2000
	s_addc_u32 s39, s39, 0
	v_add_co_u32_e32 v68, vcc, 0x1d00, v68
	s_nop 1
	v_addc_co_u32_e32 v69, vcc, 0, v69, vcc
	s_waitcnt vmcnt(22)
	v_lshlrev_b32_e32 v208, 16, v124
	v_and_b32_e32 v209, 0xffff0000, v124
	v_pk_add_f32 v[128:129], v[128:129], v[208:209]
	v_lshlrev_b32_e32 v208, 16, v125
	v_and_b32_e32 v209, 0xffff0000, v125
	v_pk_add_f32 v[130:131], v[130:131], v[208:209]
	v_lshlrev_b32_e32 v208, 16, v126
	v_and_b32_e32 v209, 0xffff0000, v126
	v_pk_add_f32 v[132:133], v[132:133], v[208:209]
	v_lshlrev_b32_e32 v208, 16, v127
	v_and_b32_e32 v209, 0xffff0000, v127
	v_pk_add_f32 v[134:135], v[134:135], v[208:209]
	v_cvt_pk_bf16_f32 v124, v128, v129
	v_cvt_pk_bf16_f32 v125, v130, v131
	v_cvt_pk_bf16_f32 v126, v132, v133
	v_cvt_pk_bf16_f32 v127, v134, v135
	s_nop 1
	v_mfma_f32_16x16x32_bf16 v[2:5], v[124:127], v[136:139], v[2:5]
	v_mfma_f32_16x16x32_bf16 v[30:33], v[124:127], v[140:143], v[30:33]
	v_mfma_f32_16x16x32_bf16 v[26:29], v[124:127], v[144:147], v[26:29]
	v_mfma_f32_16x16x32_bf16 v[22:25], v[124:127], v[148:151], v[22:25]
	v_mfma_f32_16x16x32_bf16 v[18:21], v[124:127], v[152:155], v[18:21]
	v_mfma_f32_16x16x32_bf16 v[14:17], v[124:127], v[156:159], v[14:17]
	v_mfma_f32_16x16x32_bf16 v[10:13], v[124:127], v[160:163], v[10:13]
	v_mfma_f32_16x16x32_bf16 v[6:9], v[124:127], v[164:167], v[6:9]
	global_load_dwordx4 v[124:127], v[68:69], off offset:1024
	global_load_dwordx4 v[128:131], v[70:71], off offset:512
	global_load_dwordx4 v[132:135], v[70:71], off offset:528
	global_load_dwordx4 v[136:139], v52, s[38:39] offset:0
	global_load_dwordx4 v[140:143], v52, s[38:39] offset:1024
	global_load_dwordx4 v[144:147], v52, s[38:39] offset:2048
	global_load_dwordx4 v[148:151], v52, s[38:39] offset:3072
	global_load_dwordx4 v[152:155], v54, s[38:39] offset:0
	global_load_dwordx4 v[156:159], v54, s[38:39] offset:1024
	global_load_dwordx4 v[160:163], v54, s[38:39] offset:2048
	global_load_dwordx4 v[164:167], v54, s[38:39] offset:3072
	s_add_u32 s38, s38, 0x2000
	s_addc_u32 s39, s39, 0
	s_waitcnt vmcnt(22)
; __device__ __forceinline__ float bf2f(u16 b) { return __uint_as_float(((unsigned)b) << 16); }
; __device__ void item_compress(const Params& p, int layer, int kv, int b, int g, int ct, unsigned char* smem) {
;     ...
;   for (int ii = 0; ii < 8; ++ii) {
;     const int i = wave * 8 + ii;
; #pragma unroll
;     for (int ks = 0; ks < 2; ++ks) {
;       uint4 raw = *(const uint4*)(src + (size_t)i * HS + ks * 32);
;       const float* pp = pe + i * 64 + ks * 32 + quad * 8;
;       float4 p0 = *(const float4*)pp, p1 = *(const float4*)(pp + 4);
;       bf16x8 a = pack8(bf2f((u16)(raw.x & 0xffff)) + p0.x, bf2f((u16)(raw.x >> 16)) + p0.y,
;                        bf2f((u16)(raw.y & 0xffff)) + p0.z, bf2f((u16)(raw.y >> 16)) + p0.w,
;                        bf2f((u16)(raw.z & 0xffff)) + p1.x, bf2f((u16)(raw.z >> 16)) + p1.y,
;                        bf2f((u16)(raw.w & 0xffff)) + p1.z, bf2f((u16)(raw.w >> 16)) + p1.w);
; #pragma unroll
;       for (int j = 0; j < 8; ++j) {
;         bf16x8 bfr = *(const bf16x8*)(wb + (size_t)(j * 16) * 2048 + i * 64 + ks * 32);
;         acc[j] = mfma16(a, bfr, acc[j]);
;       }
;     }
	v_lshlrev_b32_e32 v208, 16, v168
	v_and_b32_e32 v209, 0xffff0000, v168
	v_pk_add_f32 v[172:173], v[172:173], v[208:209]
	v_lshlrev_b32_e32 v208, 16, v169
	v_and_b32_e32 v209, 0xffff0000, v169
	v_pk_add_f32 v[174:175], v[174:175], v[208:209]
	v_lshlrev_b32_e32 v208, 16, v170
	v_and_b32_e32 v209, 0xffff0000, v170
	v_pk_add_f32 v[176:177], v[176:177], v[208:209]
	v_lshlrev_b32_e32 v208, 16, v171
	v_and_b32_e32 v209, 0xffff0000, v171
	v_pk_add_f32 v[178:179], v[178:179], v[208:209]
	v_cvt_pk_bf16_f32 v168, v172, v173
	v_cvt_pk_bf16_f32 v169, v174, v175
	v_cvt_pk_bf16_f32 v170, v176, v177
	v_cvt_pk_bf16_f32 v171, v178, v179
	s_nop 1
	v_mfma_f32_16x16x32_bf16 v[2:5], v[168:171], v[180:183], v[2:5]
	v_mfma_f32_16x16x32_bf16 v[30:33], v[168:171], v[184:187], v[30:33]
	v_mfma_f32_16x16x32_bf16 v[26:29], v[168:171], v[188:191], v[26:29]
	v_mfma_f32_16x16x32_bf16 v[22:25], v[168:171], v[192:195], v[22:25]
	v_mfma_f32_16x16x32_bf16 v[18:21], v[168:171], v[196:199], v[18:21]
	v_mfma_f32_16x16x32_bf16 v[14:17], v[168:171], v[200:203], v[14:17]
	v_mfma_f32_16x16x32_bf16 v[10:13], v[168:171], v[204:207], v[10:13]
	v_mfma_f32_16x16x32_bf16 v[6:9], v[168:171], v[218:221], v[6:9]
	global_load_dwordx4 v[168:171], v[68:69], off offset:1088
	global_load_dwordx4 v[172:175], v[70:71], off offset:640
	global_load_dwordx4 v[176:179], v[70:71], off offset:656
	global_load_dwordx4 v[180:183], v52, s[38:39] offset:0
	global_load_dwordx4 v[184:187], v52, s[38:39] offset:1024
	global_load_dwordx4 v[188:191], v52, s[38:39] offset:2048
	global_load_dwordx4 v[192:195], v52, s[38:39] offset:3072
	global_load_dwordx4 v[196:199], v54, s[38:39] offset:0
	global_load_dwordx4 v[200:203], v54, s[38:39] offset:1024
	global_load_dwordx4 v[204:207], v54, s[38:39] offset:2048
	global_load_dwordx4 v[218:221], v54, s[38:39] offset:3072
	s_add_u32 s38, s38, 0x2000
	s_addc_u32 s39, s39, 0
	v_add_co_u32_e32 v68, vcc, 0x1d00, v68
	s_nop 1
	v_addc_co_u32_e32 v69, vcc, 0, v69, vcc
	s_waitcnt vmcnt(22)
	v_lshlrev_b32_e32 v208, 16, v80
	v_and_b32_e32 v209, 0xffff0000, v80
	v_pk_add_f32 v[84:85], v[84:85], v[208:209]
	v_lshlrev_b32_e32 v208, 16, v81
	v_and_b32_e32 v209, 0xffff0000, v81
	v_pk_add_f32 v[86:87], v[86:87], v[208:209]
	v_lshlrev_b32_e32 v208, 16, v82
	v_and_b32_e32 v209, 0xffff0000, v82
	v_pk_add_f32 v[88:89], v[88:89], v[208:209]
	v_lshlrev_b32_e32 v208, 16, v83
	v_and_b32_e32 v209, 0xffff0000, v83
	v_pk_add_f32 v[90:91], v[90:91], v[208:209]
	v_cvt_pk_bf16_f32 v80, v84, v85
	v_cvt_pk_bf16_f32 v81, v86, v87
	v_cvt_pk_bf16_f32 v82, v88, v89
	v_cvt_pk_bf16_f32 v83, v90, v91
	s_nop 1
	v_mfma_f32_16x16x32_bf16 v[2:5], v[80:83], v[92:95], v[2:5]
	v_mfma_f32_16x16x32_bf16 v[30:33], v[80:83], v[96:99], v[30:33]
	v_mfma_f32_16x16x32_bf16 v[26:29], v[80:83], v[100:103], v[26:29]
	v_mfma_f32_16x16x32_bf16 v[22:25], v[80:83], v[104:107], v[22:25]
	v_mfma_f32_16x16x32_bf16 v[18:21], v[80:83], v[108:111], v[18:21]
	v_mfma_f32_16x16x32_bf16 v[14:17], v[80:83], v[112:115], v[14:17]
	v_mfma_f32_16x16x32_bf16 v[10:13], v[80:83], v[116:119], v[10:13]
	v_mfma_f32_16x16x32_bf16 v[6:9], v[80:83], v[120:123], v[6:9]
	global_load_dwordx4 v[80:83], v[68:69], off offset:1024
	global_load_dwordx4 v[84:87], v[70:71], off offset:768
	global_load_dwordx4 v[88:91], v[70:71], off offset:784
	global_load_dwordx4 v[92:95], v52, s[38:39] offset:0
	global_load_dwordx4 v[96:99], v52, s[38:39] offset:1024
	global_load_dwordx4 v[100:103], v52, s[38:39] offset:2048
	global_load_dwordx4 v[104:107], v52, s[38:39] offset:3072
	global_load_dwordx4 v[108:111], v54, s[38:39] offset:0
	global_load_dwordx4 v[112:115], v54, s[38:39] offset:1024
	global_load_dwordx4 v[116:119], v54, s[38:39] offset:2048
	global_load_dwordx4 v[120:123], v54, s[38:39] offset:3072
	s_add_u32 s38, s38, 0x2000
	s_addc_u32 s39, s39, 0
	s_waitcnt vmcnt(22)
	v_lshlrev_b32_e32 v208, 16, v124
	v_and_b32_e32 v209, 0xffff0000, v124
	v_pk_add_f32 v[128:129], v[128:129], v[208:209]
	v_lshlrev_b32_e32 v208, 16, v125
	v_and_b32_e32 v209, 0xffff0000, v125
	v_pk_add_f32 v[130:131], v[130:131], v[208:209]
	v_lshlrev_b32_e32 v208, 16, v126
	v_and_b32_e32 v209, 0xffff0000, v126
	v_pk_add_f32 v[132:133], v[132:133], v[208:209]
	v_lshlrev_b32_e32 v208, 16, v127
	v_and_b32_e32 v209, 0xffff0000, v127
	v_pk_add_f32 v[134:135], v[134:135], v[208:209]
	v_cvt_pk_bf16_f32 v124, v128, v129
	v_cvt_pk_bf16_f32 v125, v130, v131
	v_cvt_pk_bf16_f32 v126, v132, v133
	v_cvt_pk_bf16_f32 v127, v134, v135
	s_nop 1
	v_mfma_f32_16x16x32_bf16 v[2:5], v[124:127], v[136:139], v[2:5]
	v_mfma_f32_16x16x32_bf16 v[30:33], v[124:127], v[140:143], v[30:33]
	v_mfma_f32_16x16x32_bf16 v[26:29], v[124:127], v[144:147], v[26:29]
	v_mfma_f32_16x16x32_bf16 v[22:25], v[124:127], v[148:151], v[22:25]
	v_mfma_f32_16x16x32_bf16 v[18:21], v[124:127], v[152:155], v[18:21]
	v_mfma_f32_16x16x32_bf16 v[14:17], v[124:127], v[156:159], v[14:17]
	v_mfma_f32_16x16x32_bf16 v[10:13], v[124:127], v[160:163], v[10:13]
	v_mfma_f32_16x16x32_bf16 v[6:9], v[124:127], v[164:167], v[6:9]
	global_load_dwordx4 v[124:127], v[68:69], off offset:1088
	global_load_dwordx4 v[128:131], v[70:71], off offset:896
	global_load_dwordx4 v[132:135], v[70:71], off offset:912
	global_load_dwordx4 v[136:139], v52, s[38:39] offset:0
	global_load_dwordx4 v[140:143], v52, s[38:39] offset:1024
	global_load_dwordx4 v[144:147], v52, s[38:39] offset:2048
	global_load_dwordx4 v[148:151], v52, s[38:39] offset:3072
	global_load_dwordx4 v[152:155], v54, s[38:39] offset:0
	global_load_dwordx4 v[156:159], v54, s[38:39] offset:1024
	global_load_dwordx4 v[160:163], v54, s[38:39] offset:2048
	global_load_dwordx4 v[164:167], v54, s[38:39] offset:3072
	s_add_u32 s38, s38, 0x2000
	s_addc_u32 s39, s39, 0
	v_add_co_u32_e32 v68, vcc, 0x1d00, v68
	s_nop 1
	v_addc_co_u32_e32 v69, vcc, 0, v69, vcc
	s_waitcnt vmcnt(22)
; __device__ __forceinline__ float bf2f(u16 b) { return __uint_as_float(((unsigned)b) << 16); }
; __device__ void item_compress(const Params& p, int layer, int kv, int b, int g, int ct, unsigned char* smem) {
;     ...
;   for (int ii = 0; ii < 8; ++ii) {
;     const int i = wave * 8 + ii;
; #pragma unroll
;     for (int ks = 0; ks < 2; ++ks) {
;       uint4 raw = *(const uint4*)(src + (size_t)i * HS + ks * 32);
;       const float* pp = pe + i * 64 + ks * 32 + quad * 8;
;       float4 p0 = *(const float4*)pp, p1 = *(const float4*)(pp + 4);
;       bf16x8 a = pack8(bf2f((u16)(raw.x & 0xffff)) + p0.x, bf2f((u16)(raw.x >> 16)) + p0.y,
;                        bf2f((u16)(raw.y & 0xffff)) + p0.z, bf2f((u16)(raw.y >> 16)) + p0.w,
;                        bf2f((u16)(raw.z & 0xffff)) + p1.x, bf2f((u16)(raw.z >> 16)) + p1.y,
;                        bf2f((u16)(raw.w & 0xffff)) + p1.z, bf2f((u16)(raw.w >> 16)) + p1.w);
; #pragma unroll
;       for (int j = 0; j < 8; ++j) {
;         bf16x8 bfr = *(const bf16x8*)(wb + (size_t)(j * 16) * 2048 + i * 64 + ks * 32);
;         acc[j] = mfma16(a, bfr, acc[j]);
;       }
;     }
	v_lshlrev_b32_e32 v208, 16, v168
	v_and_b32_e32 v209, 0xffff0000, v168
	v_pk_add_f32 v[172:173], v[172:173], v[208:209]
	v_lshlrev_b32_e32 v208, 16, v169
	v_and_b32_e32 v209, 0xffff0000, v169
	v_pk_add_f32 v[174:175], v[174:175], v[208:209]
	v_lshlrev_b32_e32 v208, 16, v170
	v_and_b32_e32 v209, 0xffff0000, v170
	v_pk_add_f32 v[176:177], v[176:177], v[208:209]
	v_lshlrev_b32_e32 v208, 16, v171
	v_and_b32_e32 v209, 0xffff0000, v171
	v_pk_add_f32 v[178:179], v[178:179], v[208:209]
	v_cvt_pk_bf16_f32 v168, v172, v173
	v_cvt_pk_bf16_f32 v169, v174, v175
	v_cvt_pk_bf16_f32 v170, v176, v177
	v_cvt_pk_bf16_f32 v171, v178, v179
	s_nop 1
	v_mfma_f32_16x16x32_bf16 v[2:5], v[168:171], v[180:183], v[2:5]
	v_mfma_f32_16x16x32_bf16 v[30:33], v[168:171], v[184:187], v[30:33]
	v_mfma_f32_16x16x32_bf16 v[26:29], v[168:171], v[188:191], v[26:29]
	v_mfma_f32_16x16x32_bf16 v[22:25], v[168:171], v[192:195], v[22:25]
	v_mfma_f32_16x16x32_bf16 v[18:21], v[168:171], v[196:199], v[18:21]
	v_mfma_f32_16x16x32_bf16 v[14:17], v[168:171], v[200:203], v[14:17]
	v_mfma_f32_16x16x32_bf16 v[10:13], v[168:171], v[204:207], v[10:13]
	v_mfma_f32_16x16x32_bf16 v[6:9], v[168:171], v[218:221], v[6:9]
	global_load_dwordx4 v[168:171], v[68:69], off offset:1024
	global_load_dwordx4 v[172:175], v[70:71], off offset:1024
	global_load_dwordx4 v[176:179], v[70:71], off offset:1040
	global_load_dwordx4 v[180:183], v52, s[38:39] offset:0
	global_load_dwordx4 v[184:187], v52, s[38:39] offset:1024
	global_load_dwordx4 v[188:191], v52, s[38:39] offset:2048
	global_load_dwordx4 v[192:195], v52, s[38:39] offset:3072
	global_load_dwordx4 v[196:199], v54, s[38:39] offset:0
	global_load_dwordx4 v[200:203], v54, s[38:39] offset:1024
	global_load_dwordx4 v[204:207], v54, s[38:39] offset:2048
	global_load_dwordx4 v[218:221], v54, s[38:39] offset:3072
	s_add_u32 s38, s38, 0x2000
	s_addc_u32 s39, s39, 0
	s_waitcnt vmcnt(22)
	v_lshlrev_b32_e32 v208, 16, v80
	v_and_b32_e32 v209, 0xffff0000, v80
	v_pk_add_f32 v[84:85], v[84:85], v[208:209]
	v_lshlrev_b32_e32 v208, 16, v81
	v_and_b32_e32 v209, 0xffff0000, v81
	v_pk_add_f32 v[86:87], v[86:87], v[208:209]
	v_lshlrev_b32_e32 v208, 16, v82
	v_and_b32_e32 v209, 0xffff0000, v82
	v_pk_add_f32 v[88:89], v[88:89], v[208:209]
	v_lshlrev_b32_e32 v208, 16, v83
	v_and_b32_e32 v209, 0xffff0000, v83
	v_pk_add_f32 v[90:91], v[90:91], v[208:209]
	v_cvt_pk_bf16_f32 v80, v84, v85
	v_cvt_pk_bf16_f32 v81, v86, v87
	v_cvt_pk_bf16_f32 v82, v88, v89
	v_cvt_pk_bf16_f32 v83, v90, v91
	s_nop 1
	v_mfma_f32_16x16x32_bf16 v[2:5], v[80:83], v[92:95], v[2:5]
	v_mfma_f32_16x16x32_bf16 v[30:33], v[80:83], v[96:99], v[30:33]
	v_mfma_f32_16x16x32_bf16 v[26:29], v[80:83], v[100:103], v[26:29]
	v_mfma_f32_16x16x32_bf16 v[22:25], v[80:83], v[104:107], v[22:25]
	v_mfma_f32_16x16x32_bf16 v[18:21], v[80:83], v[108:111], v[18:21]
	v_mfma_f32_16x16x32_bf16 v[14:17], v[80:83], v[112:115], v[14:17]
	v_mfma_f32_16x16x32_bf16 v[10:13], v[80:83], v[116:119], v[10:13]
	v_mfma_f32_16x16x32_bf16 v[6:9], v[80:83], v[120:123], v[6:9]
	global_load_dwordx4 v[80:83], v[68:69], off offset:1088
	global_load_dwordx4 v[84:87], v[70:71], off offset:1152
	global_load_dwordx4 v[88:91], v[70:71], off offset:1168
	global_load_dwordx4 v[92:95], v52, s[38:39] offset:0
	global_load_dwordx4 v[96:99], v52, s[38:39] offset:1024
	global_load_dwordx4 v[100:103], v52, s[38:39] offset:2048
	global_load_dwordx4 v[104:107], v52, s[38:39] offset:3072
	global_load_dwordx4 v[108:111], v54, s[38:39] offset:0
	global_load_dwordx4 v[112:115], v54, s[38:39] offset:1024
	global_load_dwordx4 v[116:119], v54, s[38:39] offset:2048
	global_load_dwordx4 v[120:123], v54, s[38:39] offset:3072
	s_add_u32 s38, s38, 0x2000
	s_addc_u32 s39, s39, 0
	v_add_co_u32_e32 v68, vcc, 0x1d00, v68
	s_nop 1
	v_addc_co_u32_e32 v69, vcc, 0, v69, vcc
	s_waitcnt vmcnt(22)
	v_lshlrev_b32_e32 v208, 16, v124
	v_and_b32_e32 v209, 0xffff0000, v124
	v_pk_add_f32 v[128:129], v[128:129], v[208:209]
	v_lshlrev_b32_e32 v208, 16, v125
	v_and_b32_e32 v209, 0xffff0000, v125
	v_pk_add_f32 v[130:131], v[130:131], v[208:209]
	v_lshlrev_b32_e32 v208, 16, v126
	v_and_b32_e32 v209, 0xffff0000, v126
	v_pk_add_f32 v[132:133], v[132:133], v[208:209]
	v_lshlrev_b32_e32 v208, 16, v127
	v_and_b32_e32 v209, 0xffff0000, v127
	v_pk_add_f32 v[134:135], v[134:135], v[208:209]
	v_cvt_pk_bf16_f32 v124, v128, v129
	v_cvt_pk_bf16_f32 v125, v130, v131
	v_cvt_pk_bf16_f32 v126, v132, v133
	v_cvt_pk_bf16_f32 v127, v134, v135
	s_nop 1
	v_mfma_f32_16x16x32_bf16 v[2:5], v[124:127], v[136:139], v[2:5]
	v_mfma_f32_16x16x32_bf16 v[30:33], v[124:127], v[140:143], v[30:33]
	v_mfma_f32_16x16x32_bf16 v[26:29], v[124:127], v[144:147], v[26:29]
	v_mfma_f32_16x16x32_bf16 v[22:25], v[124:127], v[148:151], v[22:25]
	v_mfma_f32_16x16x32_bf16 v[18:21], v[124:127], v[152:155], v[18:21]
	v_mfma_f32_16x16x32_bf16 v[14:17], v[124:127], v[156:159], v[14:17]
	v_mfma_f32_16x16x32_bf16 v[10:13], v[124:127], v[160:163], v[10:13]
	v_mfma_f32_16x16x32_bf16 v[6:9], v[124:127], v[164:167], v[6:9]
	global_load_dwordx4 v[124:127], v[68:69], off offset:1024
	global_load_dwordx4 v[128:131], v[70:71], off offset:1280
	global_load_dwordx4 v[132:135], v[70:71], off offset:1296
	global_load_dwordx4 v[136:139], v52, s[38:39] offset:0
	global_load_dwordx4 v[140:143], v52, s[38:39] offset:1024
	global_load_dwordx4 v[144:147], v52, s[38:39] offset:2048
	global_load_dwordx4 v[148:151], v52, s[38:39] offset:3072
	global_load_dwordx4 v[152:155], v54, s[38:39] offset:0
	global_load_dwordx4 v[156:159], v54, s[38:39] offset:1024
	global_load_dwordx4 v[160:163], v54, s[38:39] offset:2048
	global_load_dwordx4 v[164:167], v54, s[38:39] offset:3072
	s_add_u32 s38, s38, 0x2000
	s_addc_u32 s39, s39, 0
	s_waitcnt vmcnt(22)
; __device__ __forceinline__ float bf2f(u16 b) { return __uint_as_float(((unsigned)b) << 16); }
; __device__ void item_compress(const Params& p, int layer, int kv, int b, int g, int ct, unsigned char* smem) {
;     ...
;   for (int ii = 0; ii < 8; ++ii) {
;     const int i = wave * 8 + ii;
; #pragma unroll
;     for (int ks = 0; ks < 2; ++ks) {
;       uint4 raw = *(const uint4*)(src + (size_t)i * HS + ks * 32);
;       const float* pp = pe + i * 64 + ks * 32 + quad * 8;
;       float4 p0 = *(const float4*)pp, p1 = *(const float4*)(pp + 4);
;       bf16x8 a = pack8(bf2f((u16)(raw.x & 0xffff)) + p0.x, bf2f((u16)(raw.x >> 16)) + p0.y,
;                        bf2f((u16)(raw.y & 0xffff)) + p0.z, bf2f((u16)(raw.y >> 16)) + p0.w,
;                        bf2f((u16)(raw.z & 0xffff)) + p1.x, bf2f((u16)(raw.z >> 16)) + p1.y,
;                        bf2f((u16)(raw.w & 0xffff)) + p1.z, bf2f((u16)(raw.w >> 16)) + p1.w);
; #pragma unroll
;       for (int j = 0; j < 8; ++j) {
;         bf16x8 bfr = *(const bf16x8*)(wb + (size_t)(j * 16) * 2048 + i * 64 + ks * 32);
;         acc[j] = mfma16(a, bfr, acc[j]);
;       }
;     }
	v_lshlrev_b32_e32 v208, 16, v168
	v_and_b32_e32 v209, 0xffff0000, v168
	v_pk_add_f32 v[172:173], v[172:173], v[208:209]
	v_lshlrev_b32_e32 v208, 16, v169
	v_and_b32_e32 v209, 0xffff0000, v169
	v_pk_add_f32 v[174:175], v[174:175], v[208:209]
	v_lshlrev_b32_e32 v208, 16, v170
	v_and_b32_e32 v209, 0xffff0000, v170
	v_pk_add_f32 v[176:177], v[176:177], v[208:209]
	v_lshlrev_b32_e32 v208, 16, v171
	v_and_b32_e32 v209, 0xffff0000, v171
	v_pk_add_f32 v[178:179], v[178:179], v[208:209]
	v_cvt_pk_bf16_f32 v168, v172, v173
	v_cvt_pk_bf16_f32 v169, v174, v175
	v_cvt_pk_bf16_f32 v170, v176, v177
	v_cvt_pk_bf16_f32 v171, v178, v179
	s_nop 1
	v_mfma_f32_16x16x32_bf16 v[2:5], v[168:171], v[180:183], v[2:5]
	v_mfma_f32_16x16x32_bf16 v[30:33], v[168:171], v[184:187], v[30:33]
	v_mfma_f32_16x16x32_bf16 v[26:29], v[168:171], v[188:191], v[26:29]
	v_mfma_f32_16x16x32_bf16 v[22:25], v[168:171], v[192:195], v[22:25]
	v_mfma_f32_16x16x32_bf16 v[18:21], v[168:171], v[196:199], v[18:21]
	v_mfma_f32_16x16x32_bf16 v[14:17], v[168:171], v[200:203], v[14:17]
	v_mfma_f32_16x16x32_bf16 v[10:13], v[168:171], v[204:207], v[10:13]
	v_mfma_f32_16x16x32_bf16 v[6:9], v[168:171], v[218:221], v[6:9]
	global_load_dwordx4 v[168:171], v[68:69], off offset:1088
	global_load_dwordx4 v[172:175], v[70:71], off offset:1408
	global_load_dwordx4 v[176:179], v[70:71], off offset:1424
	global_load_dwordx4 v[180:183], v52, s[38:39] offset:0
	global_load_dwordx4 v[184:187], v52, s[38:39] offset:1024
	global_load_dwordx4 v[188:191], v52, s[38:39] offset:2048
	global_load_dwordx4 v[192:195], v52, s[38:39] offset:3072
	global_load_dwordx4 v[196:199], v54, s[38:39] offset:0
	global_load_dwordx4 v[200:203], v54, s[38:39] offset:1024
	global_load_dwordx4 v[204:207], v54, s[38:39] offset:2048
	global_load_dwordx4 v[218:221], v54, s[38:39] offset:3072
	s_add_u32 s38, s38, 0x2000
	s_addc_u32 s39, s39, 0
	v_add_co_u32_e32 v68, vcc, 0x1d00, v68
	s_nop 1
	v_addc_co_u32_e32 v69, vcc, 0, v69, vcc
	s_waitcnt vmcnt(22)
	v_lshlrev_b32_e32 v208, 16, v80
	v_and_b32_e32 v209, 0xffff0000, v80
	v_pk_add_f32 v[84:85], v[84:85], v[208:209]
	v_lshlrev_b32_e32 v208, 16, v81
	v_and_b32_e32 v209, 0xffff0000, v81
	v_pk_add_f32 v[86:87], v[86:87], v[208:209]
	v_lshlrev_b32_e32 v208, 16, v82
	v_and_b32_e32 v209, 0xffff0000, v82
	v_pk_add_f32 v[88:89], v[88:89], v[208:209]
	v_lshlrev_b32_e32 v208, 16, v83
	v_and_b32_e32 v209, 0xffff0000, v83
	v_pk_add_f32 v[90:91], v[90:91], v[208:209]
	v_cvt_pk_bf16_f32 v80, v84, v85
	v_cvt_pk_bf16_f32 v81, v86, v87
	v_cvt_pk_bf16_f32 v82, v88, v89
	v_cvt_pk_bf16_f32 v83, v90, v91
	s_nop 1
	v_mfma_f32_16x16x32_bf16 v[2:5], v[80:83], v[92:95], v[2:5]
	v_mfma_f32_16x16x32_bf16 v[30:33], v[80:83], v[96:99], v[30:33]
	v_mfma_f32_16x16x32_bf16 v[26:29], v[80:83], v[100:103], v[26:29]
	v_mfma_f32_16x16x32_bf16 v[22:25], v[80:83], v[104:107], v[22:25]
	v_mfma_f32_16x16x32_bf16 v[18:21], v[80:83], v[108:111], v[18:21]
	v_mfma_f32_16x16x32_bf16 v[14:17], v[80:83], v[112:115], v[14:17]
	v_mfma_f32_16x16x32_bf16 v[10:13], v[80:83], v[116:119], v[10:13]
	v_mfma_f32_16x16x32_bf16 v[6:9], v[80:83], v[120:123], v[6:9]
	global_load_dwordx4 v[80:83], v[68:69], off offset:1024
	global_load_dwordx4 v[84:87], v[70:71], off offset:1536
	global_load_dwordx4 v[88:91], v[70:71], off offset:1552
	global_load_dwordx4 v[92:95], v52, s[38:39] offset:0
	global_load_dwordx4 v[96:99], v52, s[38:39] offset:1024
	global_load_dwordx4 v[100:103], v52, s[38:39] offset:2048
	global_load_dwordx4 v[104:107], v52, s[38:39] offset:3072
	global_load_dwordx4 v[108:111], v54, s[38:39] offset:0
	global_load_dwordx4 v[112:115], v54, s[38:39] offset:1024
	global_load_dwordx4 v[116:119], v54, s[38:39] offset:2048
	global_load_dwordx4 v[120:123], v54, s[38:39] offset:3072
	s_add_u32 s38, s38, 0x2000
	s_addc_u32 s39, s39, 0
	s_waitcnt vmcnt(22)
	v_lshlrev_b32_e32 v208, 16, v124
	v_and_b32_e32 v209, 0xffff0000, v124
	v_pk_add_f32 v[128:129], v[128:129], v[208:209]
	v_lshlrev_b32_e32 v208, 16, v125
	v_and_b32_e32 v209, 0xffff0000, v125
	v_pk_add_f32 v[130:131], v[130:131], v[208:209]
	v_lshlrev_b32_e32 v208, 16, v126
	v_and_b32_e32 v209, 0xffff0000, v126
	v_pk_add_f32 v[132:133], v[132:133], v[208:209]
	v_lshlrev_b32_e32 v208, 16, v127
	v_and_b32_e32 v209, 0xffff0000, v127
	v_pk_add_f32 v[134:135], v[134:135], v[208:209]
	v_cvt_pk_bf16_f32 v124, v128, v129
	v_cvt_pk_bf16_f32 v125, v130, v131
	v_cvt_pk_bf16_f32 v126, v132, v133
	v_cvt_pk_bf16_f32 v127, v134, v135
	s_nop 1
	v_mfma_f32_16x16x32_bf16 v[2:5], v[124:127], v[136:139], v[2:5]
	v_mfma_f32_16x16x32_bf16 v[30:33], v[124:127], v[140:143], v[30:33]
	v_mfma_f32_16x16x32_bf16 v[26:29], v[124:127], v[144:147], v[26:29]
	v_mfma_f32_16x16x32_bf16 v[22:25], v[124:127], v[148:151], v[22:25]
	v_mfma_f32_16x16x32_bf16 v[18:21], v[124:127], v[152:155], v[18:21]
	v_mfma_f32_16x16x32_bf16 v[14:17], v[124:127], v[156:159], v[14:17]
	v_mfma_f32_16x16x32_bf16 v[10:13], v[124:127], v[160:163], v[10:13]
	v_mfma_f32_16x16x32_bf16 v[6:9], v[124:127], v[164:167], v[6:9]
	global_load_dwordx4 v[124:127], v[68:69], off offset:1088
	global_load_dwordx4 v[128:131], v[70:71], off offset:1664
	global_load_dwordx4 v[132:135], v[70:71], off offset:1680
	global_load_dwordx4 v[136:139], v52, s[38:39] offset:0
	global_load_dwordx4 v[140:143], v52, s[38:39] offset:1024
	global_load_dwordx4 v[144:147], v52, s[38:39] offset:2048
	global_load_dwordx4 v[148:151], v52, s[38:39] offset:3072
	global_load_dwordx4 v[152:155], v54, s[38:39] offset:0
	global_load_dwordx4 v[156:159], v54, s[38:39] offset:1024
	global_load_dwordx4 v[160:163], v54, s[38:39] offset:2048
	global_load_dwordx4 v[164:167], v54, s[38:39] offset:3072
	s_add_u32 s38, s38, 0x2000
	s_addc_u32 s39, s39, 0
	v_add_co_u32_e32 v68, vcc, 0x1d00, v68
	s_nop 1
	v_addc_co_u32_e32 v69, vcc, 0, v69, vcc
	s_waitcnt vmcnt(22)
; __device__ __forceinline__ float bf2f(u16 b) { return __uint_as_float(((unsigned)b) << 16); }
; __device__ void item_compress(const Params& p, int layer, int kv, int b, int g, int ct, unsigned char* smem) {
;     ...
;   for (int ii = 0; ii < 8; ++ii) {
;     const int i = wave * 8 + ii;
; #pragma unroll
;     for (int ks = 0; ks < 2; ++ks) {
;       uint4 raw = *(const uint4*)(src + (size_t)i * HS + ks * 32);
;       const float* pp = pe + i * 64 + ks * 32 + quad * 8;
;       float4 p0 = *(const float4*)pp, p1 = *(const float4*)(pp + 4);
;       bf16x8 a = pack8(bf2f((u16)(raw.x & 0xffff)) + p0.x, bf2f((u16)(raw.x >> 16)) + p0.y,
;                        bf2f((u16)(raw.y & 0xffff)) + p0.z, bf2f((u16)(raw.y >> 16)) + p0.w,
;                        bf2f((u16)(raw.z & 0xffff)) + p1.x, bf2f((u16)(raw.z >> 16)) + p1.y,
;                        bf2f((u16)(raw.w & 0xffff)) + p1.z, bf2f((u16)(raw.w >> 16)) + p1.w);
; #pragma unroll
;       for (int j = 0; j < 8; ++j) {
;         bf16x8 bfr = *(const bf16x8*)(wb + (size_t)(j * 16) * 2048 + i * 64 + ks * 32);
;         acc[j] = mfma16(a, bfr, acc[j]);
;       }
;     }
	v_lshlrev_b32_e32 v208, 16, v168
	v_and_b32_e32 v209, 0xffff0000, v168
	v_pk_add_f32 v[172:173], v[172:173], v[208:209]
	v_lshlrev_b32_e32 v208, 16, v169
	v_and_b32_e32 v209, 0xffff0000, v169
	v_pk_add_f32 v[174:175], v[174:175], v[208:209]
	v_lshlrev_b32_e32 v208, 16, v170
	v_and_b32_e32 v209, 0xffff0000, v170
	v_pk_add_f32 v[176:177], v[176:177], v[208:209]
	v_lshlrev_b32_e32 v208, 16, v171
	v_and_b32_e32 v209, 0xffff0000, v171
	v_pk_add_f32 v[178:179], v[178:179], v[208:209]
	v_cvt_pk_bf16_f32 v168, v172, v173
	v_cvt_pk_bf16_f32 v169, v174, v175
	v_cvt_pk_bf16_f32 v170, v176, v177
	v_cvt_pk_bf16_f32 v171, v178, v179
	s_nop 1
	v_mfma_f32_16x16x32_bf16 v[2:5], v[168:171], v[180:183], v[2:5]
	v_mfma_f32_16x16x32_bf16 v[30:33], v[168:171], v[184:187], v[30:33]
	v_mfma_f32_16x16x32_bf16 v[26:29], v[168:171], v[188:191], v[26:29]
	v_mfma_f32_16x16x32_bf16 v[22:25], v[168:171], v[192:195], v[22:25]
	v_mfma_f32_16x16x32_bf16 v[18:21], v[168:171], v[196:199], v[18:21]
	v_mfma_f32_16x16x32_bf16 v[14:17], v[168:171], v[200:203], v[14:17]
	v_mfma_f32_16x16x32_bf16 v[10:13], v[168:171], v[204:207], v[10:13]
	v_mfma_f32_16x16x32_bf16 v[6:9], v[168:171], v[218:221], v[6:9]
	global_load_dwordx4 v[168:171], v[68:69], off offset:1024
	global_load_dwordx4 v[172:175], v[70:71], off offset:1792
	global_load_dwordx4 v[176:179], v[70:71], off offset:1808
	global_load_dwordx4 v[180:183], v52, s[38:39] offset:0
	global_load_dwordx4 v[184:187], v52, s[38:39] offset:1024
	global_load_dwordx4 v[188:191], v52, s[38:39] offset:2048
	global_load_dwordx4 v[192:195], v52, s[38:39] offset:3072
	global_load_dwordx4 v[196:199], v54, s[38:39] offset:0
	global_load_dwordx4 v[200:203], v54, s[38:39] offset:1024
	global_load_dwordx4 v[204:207], v54, s[38:39] offset:2048
	global_load_dwordx4 v[218:221], v54, s[38:39] offset:3072
	s_add_u32 s38, s38, 0x2000
	s_addc_u32 s39, s39, 0
	s_waitcnt vmcnt(22)
	v_lshlrev_b32_e32 v208, 16, v80
	v_and_b32_e32 v209, 0xffff0000, v80
	v_pk_add_f32 v[84:85], v[84:85], v[208:209]
	v_lshlrev_b32_e32 v208, 16, v81
	v_and_b32_e32 v209, 0xffff0000, v81
	v_pk_add_f32 v[86:87], v[86:87], v[208:209]
	v_lshlrev_b32_e32 v208, 16, v82
	v_and_b32_e32 v209, 0xffff0000, v82
	v_pk_add_f32 v[88:89], v[88:89], v[208:209]
	v_lshlrev_b32_e32 v208, 16, v83
	v_and_b32_e32 v209, 0xffff0000, v83
	v_pk_add_f32 v[90:91], v[90:91], v[208:209]
	v_cvt_pk_bf16_f32 v80, v84, v85
	v_cvt_pk_bf16_f32 v81, v86, v87
	v_cvt_pk_bf16_f32 v82, v88, v89
	v_cvt_pk_bf16_f32 v83, v90, v91
	s_nop 1
	v_mfma_f32_16x16x32_bf16 v[2:5], v[80:83], v[92:95], v[2:5]
	v_mfma_f32_16x16x32_bf16 v[30:33], v[80:83], v[96:99], v[30:33]
	v_mfma_f32_16x16x32_bf16 v[26:29], v[80:83], v[100:103], v[26:29]
	v_mfma_f32_16x16x32_bf16 v[22:25], v[80:83], v[104:107], v[22:25]
	v_mfma_f32_16x16x32_bf16 v[18:21], v[80:83], v[108:111], v[18:21]
	v_mfma_f32_16x16x32_bf16 v[14:17], v[80:83], v[112:115], v[14:17]
	v_mfma_f32_16x16x32_bf16 v[10:13], v[80:83], v[116:119], v[10:13]
	v_mfma_f32_16x16x32_bf16 v[6:9], v[80:83], v[120:123], v[6:9]
	global_load_dwordx4 v[80:83], v[68:69], off offset:1088
	global_load_dwordx4 v[84:87], v[70:71], off offset:1920
	global_load_dwordx4 v[88:91], v[70:71], off offset:1936
	global_load_dwordx4 v[92:95], v52, s[38:39] offset:0
	global_load_dwordx4 v[96:99], v52, s[38:39] offset:1024
	global_load_dwordx4 v[100:103], v52, s[38:39] offset:2048
	global_load_dwordx4 v[104:107], v52, s[38:39] offset:3072
	global_load_dwordx4 v[108:111], v54, s[38:39] offset:0
	global_load_dwordx4 v[112:115], v54, s[38:39] offset:1024
	global_load_dwordx4 v[116:119], v54, s[38:39] offset:2048
	global_load_dwordx4 v[120:123], v54, s[38:39] offset:3072
	s_add_u32 s38, s38, 0x2000
	s_addc_u32 s39, s39, 0
	s_waitcnt vmcnt(22)
	v_lshlrev_b32_e32 v208, 16, v124
	v_and_b32_e32 v209, 0xffff0000, v124
	v_pk_add_f32 v[128:129], v[128:129], v[208:209]
	v_lshlrev_b32_e32 v208, 16, v125
	v_and_b32_e32 v209, 0xffff0000, v125
	v_pk_add_f32 v[130:131], v[130:131], v[208:209]
	v_lshlrev_b32_e32 v208, 16, v126
	v_and_b32_e32 v209, 0xffff0000, v126
	v_pk_add_f32 v[132:133], v[132:133], v[208:209]
	v_lshlrev_b32_e32 v208, 16, v127
	v_and_b32_e32 v209, 0xffff0000, v127
	v_pk_add_f32 v[134:135], v[134:135], v[208:209]
	v_cvt_pk_bf16_f32 v124, v128, v129
	v_cvt_pk_bf16_f32 v125, v130, v131
	v_cvt_pk_bf16_f32 v126, v132, v133
	v_cvt_pk_bf16_f32 v127, v134, v135
	s_nop 1
	v_mfma_f32_16x16x32_bf16 v[2:5], v[124:127], v[136:139], v[2:5]
	v_mfma_f32_16x16x32_bf16 v[30:33], v[124:127], v[140:143], v[30:33]
	v_mfma_f32_16x16x32_bf16 v[26:29], v[124:127], v[144:147], v[26:29]
	v_mfma_f32_16x16x32_bf16 v[22:25], v[124:127], v[148:151], v[22:25]
	v_mfma_f32_16x16x32_bf16 v[18:21], v[124:127], v[152:155], v[18:21]
	v_mfma_f32_16x16x32_bf16 v[14:17], v[124:127], v[156:159], v[14:17]
	v_mfma_f32_16x16x32_bf16 v[10:13], v[124:127], v[160:163], v[10:13]
	v_mfma_f32_16x16x32_bf16 v[6:9], v[124:127], v[164:167], v[6:9]
	s_waitcnt vmcnt(11)
	v_lshlrev_b32_e32 v208, 16, v168
	v_and_b32_e32 v209, 0xffff0000, v168
	v_pk_add_f32 v[172:173], v[172:173], v[208:209]
	v_lshlrev_b32_e32 v208, 16, v169
	v_and_b32_e32 v209, 0xffff0000, v169
	v_pk_add_f32 v[174:175], v[174:175], v[208:209]
	v_lshlrev_b32_e32 v208, 16, v170
	v_and_b32_e32 v209, 0xffff0000, v170
	v_pk_add_f32 v[176:177], v[176:177], v[208:209]
	v_lshlrev_b32_e32 v208, 16, v171
	v_and_b32_e32 v209, 0xffff0000, v171
	v_pk_add_f32 v[178:179], v[178:179], v[208:209]
	v_cvt_pk_bf16_f32 v168, v172, v173
	v_cvt_pk_bf16_f32 v169, v174, v175
	v_cvt_pk_bf16_f32 v170, v176, v177
	v_cvt_pk_bf16_f32 v171, v178, v179
	s_nop 1
	v_mfma_f32_16x16x32_bf16 v[2:5], v[168:171], v[180:183], v[2:5]
	v_mfma_f32_16x16x32_bf16 v[30:33], v[168:171], v[184:187], v[30:33]
	v_mfma_f32_16x16x32_bf16 v[26:29], v[168:171], v[188:191], v[26:29]
	v_mfma_f32_16x16x32_bf16 v[22:25], v[168:171], v[192:195], v[22:25]
	v_mfma_f32_16x16x32_bf16 v[18:21], v[168:171], v[196:199], v[18:21]
	v_mfma_f32_16x16x32_bf16 v[14:17], v[168:171], v[200:203], v[14:17]
	v_mfma_f32_16x16x32_bf16 v[10:13], v[168:171], v[204:207], v[10:13]
	v_mfma_f32_16x16x32_bf16 v[6:9], v[168:171], v[218:221], v[6:9]
	s_waitcnt vmcnt(0)
; __device__ void item_compress(const Params& p, int layer, int kv, int b, int g, int ct, unsigned char* smem) {
;     ...
;       for (int j = 0; j < 8; ++j) {
;         bf16x8 bfr = *(const bf16x8*)(wb + (size_t)(j * 16) * 2048 + i * 64 + ks * 32);
;         acc[j] = mfma16(a, bfr, acc[j]);
;       }
;     }
;   }
;   __syncthreads();
; #pragma unroll
;   for (int j = 0; j < 8; ++j)
; #pragma unroll
;     for (int r = 0; r < 4; ++r) sP[(wave * 16 + quad * 4 + r) * 132 + j * 16 + l15] = acc[j][r];
;   __syncthreads();
	v_lshlrev_b32_e32 v208, 16, v80
	v_and_b32_e32 v209, 0xffff0000, v80
	v_pk_add_f32 v[84:85], v[84:85], v[208:209]
	v_lshlrev_b32_e32 v208, 16, v81
	v_and_b32_e32 v209, 0xffff0000, v81
	v_pk_add_f32 v[86:87], v[86:87], v[208:209]
	v_lshlrev_b32_e32 v208, 16, v82
	v_and_b32_e32 v209, 0xffff0000, v82
	v_pk_add_f32 v[88:89], v[88:89], v[208:209]
	v_lshlrev_b32_e32 v208, 16, v83
	v_and_b32_e32 v209, 0xffff0000, v83
	v_pk_add_f32 v[90:91], v[90:91], v[208:209]
	v_cvt_pk_bf16_f32 v80, v84, v85
	v_cvt_pk_bf16_f32 v81, v86, v87
	v_cvt_pk_bf16_f32 v82, v88, v89
	v_cvt_pk_bf16_f32 v83, v90, v91
	s_nop 1
	v_mfma_f32_16x16x32_bf16 v[2:5], v[80:83], v[92:95], v[2:5]
	v_mfma_f32_16x16x32_bf16 v[30:33], v[80:83], v[96:99], v[30:33]
	v_mfma_f32_16x16x32_bf16 v[26:29], v[80:83], v[100:103], v[26:29]
	v_mfma_f32_16x16x32_bf16 v[22:25], v[80:83], v[104:107], v[22:25]
	v_mfma_f32_16x16x32_bf16 v[18:21], v[80:83], v[108:111], v[18:21]
	v_mfma_f32_16x16x32_bf16 v[14:17], v[80:83], v[112:115], v[14:17]
	v_mfma_f32_16x16x32_bf16 v[10:13], v[80:83], v[116:119], v[10:13]
	v_mfma_f32_16x16x32_bf16 v[6:9], v[80:83], v[120:123], v[6:9]
	v_and_b32_e32 v34, 3, v74
	v_lshlrev_b32_e32 v35, 4, v75
	v_lshlrev_b32_e32 v36, 2, v34
	v_or_b32_e32 v0, v36, v35
	s_movk_i32 s39, 0x210
	v_mul_lo_u32 v0, v0, s39
	v_lshl_or_b32 v0, v72, 2, v0
	s_waitcnt lgkmcnt(0)
	s_barrier
	ds_write2_b32 v0, v2, v30 offset1:16
	ds_write2_b32 v0, v3, v31 offset0:132 offset1:148
	v_add_u32_e32 v2, 0x400, v0
	ds_write2_b32 v2, v4, v32 offset0:8 offset1:24
	ds_write2_b32 v2, v5, v33 offset0:140 offset1:156
	ds_write2_b32 v0, v26, v22 offset0:32 offset1:48
	ds_write2_b32 v0, v27, v23 offset0:164 offset1:180
	ds_write2_b32 v2, v28, v24 offset0:40 offset1:56
	ds_write2_b32 v2, v29, v25 offset0:172 offset1:188
	ds_write2_b32 v0, v18, v14 offset0:64 offset1:80
	ds_write2_b32 v0, v19, v15 offset0:196 offset1:212
	ds_write2_b32 v2, v20, v16 offset0:72 offset1:88
	ds_write2_b32 v2, v21, v17 offset0:204 offset1:220
	ds_write2_b32 v0, v10, v6 offset0:96 offset1:112
	ds_write2_b32 v0, v11, v7 offset0:228 offset1:244
	ds_write2_b32 v2, v12, v8 offset0:104 offset1:120
	ds_write2_b32 v2, v13, v9 offset0:236 offset1:252
	v_and_b32_e32 v6, 0x7f, v73
	s_and_b32 s38, s40, 1
	v_lshlrev_b32_e32 v0, 2, v6
	v_ashrrev_i32_e32 v8, 7, v73
	s_and_b64 s[30:31], s[30:31], exec
	v_mad_u64_u32 v[2:3], s[30:31], v8, s39, v[0:1]
	s_waitcnt lgkmcnt(0)
	s_barrier
; __device__ __forceinline__ float silu_f(float x) { return x * __builtin_amdgcn_rcpf(1.f + __expf(-x)); }
; __device__ void item_compress(const Params& p, int layer, int kv, int b, int g, int ct, unsigned char* smem) {
;     ...
; #pragma unroll
;   for (int e = 0; e < 8; ++e) {
;     int idx = e * 256 + tid;
;     int row = idx >> 7, cc = idx & 127;
;     float v = ((sP[row * 132 + cc] + sP[(16 + row) * 132 + cc]) + sP[(32 + row) * 132 + cc]) + sP[(48 + row) * 132 + cc];
;     v = silu_f(v);
;     sH[row * 136 + cc] = (u16)(pack2(v, 0.f) & 0xffff);
;   }
;   __syncthreads();
;   f32x4 a2 = f32x4{0.f, 0.f, 0.f, 0.f};
; #pragma unroll
;   for (int ks = 0; ks < 4; ++ks) {
;     bf16x8 a = *(const bf16x8*)(sH + l15 * 136 + ks * 32 + quad * 8);
;     bf16x8 bb = *(const bf16x8*)(w2t + (size_t)(wave * 16 + l15) * 128 + ks * 32 + quad * 8);
;     a2 = mfma16(a, bb, a2);
;   }
;   const int d = wave * 16 + l15;
;   const int cc = c0 + quad * 4;
;   float v0 = a2[0], v1 = a2[1], v2 = a2[2], v3 = (cc + 3 < 127) ? a2[3] : 0.f;
	ds_read2st64_b32 v[4:5], v2 offset1:33
	ds_read2st64_b32 v[2:3], v2 offset0:66 offset1:99
	v_lshlrev_b32_e32 v6, 1, v6
	s_mov_b32 s30, 0x2904400
	s_cselect_b32 s30, s30, 0x2914400
	s_waitcnt lgkmcnt(1)
	v_add_f32_e32 v4, v4, v5
	s_waitcnt lgkmcnt(0)
	v_add_f32_e32 v2, v4, v2
	v_add_f32_e32 v7, v2, v3
	v_mul_f32_e32 v2, 0xbfb8aa3b, v7
	v_exp_f32_e32 v9, v2
	v_add_u32_e32 v2, 0x100, v73
	v_ashrrev_i32_e32 v10, 7, v2
	v_mad_u64_u32 v[2:3], s[40:41], v10, s39, v[0:1]
	ds_read2st64_b32 v[4:5], v2 offset1:33
	ds_read2st64_b32 v[2:3], v2 offset0:66 offset1:99
	v_add_f32_e32 v9, 1.0, v9
	v_rcp_f32_e32 v9, v9
	s_add_u32 s30, s9, s30
	s_waitcnt lgkmcnt(1)
	v_add_f32_e32 v4, v4, v5
	s_waitcnt lgkmcnt(0)
	v_add_f32_e32 v2, v4, v2
	v_add_f32_e32 v3, v2, v3
	v_mul_f32_e32 v2, 0xbfb8aa3b, v3
	v_exp_f32_e32 v4, v2
	v_mul_f32_e32 v5, v7, v9
	v_cvt_pk_bf16_f32 v11, v5, s0
	v_sub_u32_e32 v2, v0, v6
	v_add_f32_e32 v4, 1.0, v4
	v_rcp_f32_e32 v12, v4
	v_add_u32_e32 v4, 0x200, v73
	v_ashrrev_i32_e32 v13, 7, v4
	v_mad_u64_u32 v[4:5], s[40:41], v13, s39, v[0:1]
	ds_read2st64_b32 v[6:7], v4 offset1:33
	ds_read2st64_b32 v[4:5], v4 offset0:66 offset1:99
	v_mad_u64_u32 v[8:9], s[40:41], v8, s5, v[2:3]
	ds_write_b16 v8, v11 offset:33792
	s_waitcnt lgkmcnt(2)
	v_add_f32_e32 v6, v6, v7
	s_waitcnt lgkmcnt(1)
	v_add_f32_e32 v4, v6, v4
	v_add_f32_e32 v11, v4, v5
	v_mul_f32_e32 v4, 0xbfb8aa3b, v11
	v_exp_f32_e32 v6, v4
	v_mul_f32_e32 v3, v3, v12
	v_cvt_pk_bf16_f32 v3, v3, s0
	v_mad_u64_u32 v[4:5], s[40:41], v10, s5, v[2:3]
	v_add_f32_e32 v5, 1.0, v6
	v_add_u32_e32 v6, 0x300, v73
	v_ashrrev_i32_e32 v10, 7, v6
	v_mad_u64_u32 v[6:7], s[40:41], v10, s39, v[0:1]
	ds_read2st64_b32 v[8:9], v6 offset1:33
	ds_read2st64_b32 v[6:7], v6 offset0:66 offset1:99
	v_rcp_f32_e32 v5, v5
	ds_write_b16 v4, v3 offset:33792
	s_addc_u32 s31, s12, 0
	s_waitcnt lgkmcnt(2)
	v_add_f32_e32 v4, v8, v9
	s_waitcnt lgkmcnt(1)
	v_add_f32_e32 v4, v4, v6
	v_mul_f32_e32 v3, v11, v5
	v_add_f32_e32 v11, v4, v7
	v_mul_f32_e32 v4, 0xbfb8aa3b, v11
	v_exp_f32_e32 v12, v4
	v_add_u32_e32 v4, 0x400, v73
	v_ashrrev_i32_e32 v14, 7, v4
	v_mad_u64_u32 v[4:5], s[40:41], v14, s39, v[0:1]
	ds_read2st64_b32 v[6:7], v4 offset1:33
	ds_read2st64_b32 v[4:5], v4 offset0:66 offset1:99
	v_cvt_pk_bf16_f32 v3, v3, s0
	v_mad_u64_u32 v[8:9], s[40:41], v13, s5, v[2:3]
	s_waitcnt lgkmcnt(1)
	v_add_f32_e32 v6, v6, v7
	s_waitcnt lgkmcnt(0)
	v_add_f32_e32 v4, v6, v4
	v_add_f32_e32 v9, 1.0, v12
	v_add_f32_e32 v12, v4, v5
	v_mul_f32_e32 v4, 0xbfb8aa3b, v12
	v_exp_f32_e32 v4, v4
	v_rcp_f32_e32 v9, v9
	ds_write_b16 v8, v3 offset:33792
	v_add_f32_e32 v4, 1.0, v4
	v_mul_f32_e32 v3, v11, v9
	v_rcp_f32_e32 v11, v4
	v_add_u32_e32 v4, 0x500, v73
	v_ashrrev_i32_e32 v13, 7, v4
	v_mad_u64_u32 v[4:5], s[40:41], v13, s39, v[0:1]
	ds_read2st64_b32 v[6:7], v4 offset1:33
	ds_read2st64_b32 v[4:5], v4 offset0:66 offset1:99
	v_cvt_pk_bf16_f32 v3, v3, s0
	v_mad_u64_u32 v[8:9], s[40:41], v10, s5, v[2:3]
	s_waitcnt lgkmcnt(1)
	v_add_f32_e32 v6, v6, v7
	s_waitcnt lgkmcnt(0)
	v_add_f32_e32 v4, v6, v4
	v_add_f32_e32 v10, v4, v5
	v_mul_f32_e32 v4, 0xbfb8aa3b, v10
	v_exp_f32_e32 v6, v4
	ds_write_b16 v8, v3 offset:33792
	v_mul_f32_e32 v3, v12, v11
	v_cvt_pk_bf16_f32 v3, v3, s0
	v_mad_u64_u32 v[4:5], s[40:41], v14, s5, v[2:3]
	v_add_f32_e32 v5, 1.0, v6
	v_add_u32_e32 v6, 0x600, v73
	v_ashrrev_i32_e32 v11, 7, v6
	v_mad_u64_u32 v[6:7], s[40:41], v11, s39, v[0:1]
	ds_read2st64_b32 v[8:9], v6 offset1:33
	ds_read2st64_b32 v[6:7], v6 offset0:66 offset1:99
	v_rcp_f32_e32 v5, v5
	ds_write_b16 v4, v3 offset:33792
	s_waitcnt lgkmcnt(2)
	v_add_f32_e32 v4, v8, v9
	s_waitcnt lgkmcnt(1)
	v_add_f32_e32 v4, v4, v6
	v_mul_f32_e32 v3, v10, v5
	v_add_f32_e32 v10, v4, v7
	v_mul_f32_e32 v4, 0xbfb8aa3b, v10
	v_exp_f32_e32 v12, v4
	v_add_u32_e32 v4, 0x700, v73
	v_ashrrev_i32_e32 v14, 7, v4
	v_mad_u64_u32 v[4:5], s[40:41], v14, s39, v[0:1]
	ds_read2st64_b32 v[6:7], v4 offset1:33
	ds_read2st64_b32 v[4:5], v4 offset0:66 offset1:99
	v_cvt_pk_bf16_f32 v3, v3, s0
	v_mad_u64_u32 v[8:9], s[40:41], v13, s5, v[2:3]
	s_waitcnt lgkmcnt(1)
	v_add_f32_e32 v6, v6, v7
	s_waitcnt lgkmcnt(0)
	v_add_f32_e32 v4, v6, v4
	v_add_f32_e32 v6, v4, v5
	v_mul_f32_e32 v4, 0xbfb8aa3b, v6
	v_exp_f32_e32 v4, v4
	v_add_f32_e32 v0, 1.0, v12
	v_rcp_f32_e32 v0, v0
	ds_write_b16 v8, v3 offset:33792
	v_add_f32_e32 v3, 1.0, v4
	v_rcp_f32_e32 v3, v3
	v_mul_f32_e32 v0, v10, v0
	v_cvt_pk_bf16_f32 v0, v0, s0
	v_mad_u64_u32 v[4:5], s[40:41], v11, s5, v[2:3]
	ds_write_b16 v4, v0 offset:33792
	v_mul_f32_e32 v0, v6, v3
	v_or_b32_e32 v6, v35, v72
	v_cvt_pk_bf16_f32 v0, v0, s0
	v_mad_u64_u32 v[2:3], s[40:41], v14, s5, v[2:3]
	v_ashrrev_i32_e32 v7, 31, v6
	ds_write_b16 v2, v0 offset:33792
	v_lshlrev_b64 v[2:3], 8, v[6:7]
	v_lshlrev_b32_e32 v0, 4, v34
	v_lshl_add_u64 v[2:3], s[30:31], 0, v[2:3]
	v_lshl_add_u64 v[16:17], v[2:3], 0, v[0:1]
	s_waitcnt lgkmcnt(0)
	s_barrier
	global_load_dwordx4 v[2:5], v[16:17], off
	global_load_dwordx4 v[8:11], v[16:17], off offset:64
	global_load_dwordx4 v[12:15], v[16:17], off offset:128
	s_nop 0
	global_load_dwordx4 v[16:19], v[16:17], off offset:192
	v_mad_u32_u24 v0, v72, s5, v0
	ds_read_b128 v[20:23], v0 offset:33792
	ds_read_b128 v[24:27], v0 offset:33856
	s_movk_i32 s30, 0x7c
	s_waitcnt vmcnt(3) lgkmcnt(1)
	v_mfma_f32_16x16x32_bf16 v[2:5], v[20:23], v[2:5], 0
	ds_read_b128 v[20:23], v0 offset:33920
	s_waitcnt vmcnt(2) lgkmcnt(1)
	v_mfma_f32_16x16x32_bf16 v[2:5], v[24:27], v[8:11], v[2:5]
	ds_read_b128 v[8:11], v0 offset:33984
	s_waitcnt vmcnt(1) lgkmcnt(1)
	v_mfma_f32_16x16x32_bf16 v[2:5], v[20:23], v[12:15], v[2:5]
	s_waitcnt vmcnt(0) lgkmcnt(0)
	v_mfma_f32_16x16x32_bf16 v[2:5], v[8:11], v[16:19], v[2:5]
	v_or_b32_e32 v11, s35, v36
	v_cmp_ne_u32_e32 vcc, s30, v11
	s_mov_b64 s[30:31], -1
	s_nop 4
	v_cndmask_b32_e32 v10, 0, v5, vcc
	s_and_b64 vcc, exec, s[18:19]
	v_cvt_pk_bf16_f32 v8, v2, v3
	s_cbranch_vccnz .LBB0_236
	s_andn2_b64 vcc, exec, s[30:31]
	s_cbranch_vccnz .LBB0_231
	s_branch .LBB0_237

;     ...
;   if (kt >= kt_end) { hook(); return; }
;   const bf16x8 ones = bf16x8{0x3F80, 0x3F80, 0x3F80, 0x3F80, 0x3F80, 0x3F80, 0x3F80, 0x3F80};
;   f32x4 L[NQ * NMAP];
; #pragma unroll
;   for (int i = 0; i < NQ * NMAP; ++i) L[i] = f32x4{0.f, 0.f, 0.f, 0.f};
;   int nxt = next_tile(kt);
;   {
;     u32x4 fk[TK][2], fv[TK][2];
; #pragma unroll
;     for (int t = 0; t < TK; ++t)
; #pragma unroll
;       for (int i = 0; i < 2; ++i) {
;         fk[t][i] = *(const u32x4*)(gk + (size_t)((kt + t) * 64 + i * 32) * kstride);
;         fv[t][i] = *(const u32x4*)(gv + (size_t)(i * 32) * vtstride + (kt + t) * 64);
;       }
;     if (nxt < kt_end) gload(nxt);
;     hook();
;     __syncthreads();
; #pragma unroll
;     for (int t = 0; t < TK; ++t)
; #pragma unroll
;       for (int i = 0; i < 2; ++i) {
;         *(u32x4*)(wk + t * TSZ + i * 32 * 64) = fk[t][i];
;         *(u32x4*)(wv + t * TSZ + i * 32 * 72) = fv[t][i];
;       }
;   }
;   __syncthreads();
; __device__ void item_swa(const Params& p, int layer, int b, int g, int qt, unsigned char* smem) {
;     ...
;   const float slope2 = exp2f(-2.f * (float)(hh + 1)) * LOG2E;
;   const unsigned selq[2] = {0xffffffffu, 0xffffffffu};
;   const float c1 = 0.125f * LOG2E;
;   const u16* hb = P_H + (size_t)b * SEQ * HS;
;   const u16* vt = P_VT + ((size_t)b * VTC + 256 + g * 64) * SEQ;
;   bf16x8 qf[2][2];
; #pragma unroll
;   for (int n = 0; n < 2; ++n)
; #pragma unroll
;     for (int ks = 0; ks < 2; ++ks)
;       qf[n][ks] = *(const bf16x8*)(hb + (size_t)tq[n] * HS + C_QB + hh * 64 + ks * 32 + quad * 8);
;   uint2 gpre[2][4];
; #pragma unroll
;   for (int n = 0; n < 2; ++n)
; #pragma unroll
;     for (int dt = 0; dt < 4; ++dt)
;       gpre[n][dt] = *(const uint2*)(hb + (size_t)tq[n] * HS + C_GB + hh * 64 + dt * 16 + quad * 4);
;   f32x4 O[2][4];
;   float l[2] = {0.f, 0.f};
; #pragma unroll
;   for (int n = 0; n < 2; ++n)
; #pragma unroll
;     for (int dt = 0; dt < 4; ++dt) O[n][dt] = f32x4{0.f, 0.f, 0.f, 0.f};
;   int ktb = qt - 2; if (ktb < 0) ktb = 0;
;   int kte = qt + 1;
;     ...
;   flash_pass<false, 1, 2, 2>(hb + C_KB + g * 64, HS, vt, SEQ, ktb, kte, 0u, qf, tq, qlo, qlo + 31, slope2, 128, selq, c1,
;                              O, l, sK, sVt);
.LBB0_251:
	v_lshrrev_b32_e32 v86, 4, v85
	v_xor_b32_e32 v89, v86, v85
	v_lshlrev_b32_e32 v88, 7, v30
	v_lshlrev_b32_e32 v89, 4, v89
	s_movk_i32 s0, 0x70
	v_and_or_b32 v181, v89, s0, v88
	s_add_i32 s0, s25, 1
	v_cvt_f32_i32_e32 v89, s0
	v_lshlrev_b32_e32 v30, 4, v30
	s_and_b32 s0, s24, 31
	v_add3_u32 v182, v88, v30, v0
	s_lshl_b32 s30, s0, 6
	v_mul_f32_e32 v0, -2.0, v89
	s_mov_b32 s0, 0xc2fc0000
	v_cmp_gt_f32_e32 vcc, s0, v0
	s_or_b32 s59, s35, 31
	s_and_b64 s[0:1], vcc, exec
	v_cndmask_b32_e32 v0, 0, v213, vcc
	v_fmac_f32_e32 v0, -2.0, v89
	v_exp_f32_e32 v0, v0
	s_cselect_b32 s0, 0xffffffc0, 0
	v_bfe_u32 v87, v85, 4, 2
	v_ldexp_f32 v0, v0, s0
	v_mul_f32_e32 v183, 0x3fb8aa3b, v0
	s_mov_b64 s[0:1], 0x20000
	v_bfe_u32 v0, v85, 1, 3
	s_barrier
	s_waitcnt vmcnt(7)
	ds_write_b128 v181, v[2:5]
	s_waitcnt vmcnt(6)
	ds_write_b128 v182, v[6:9] offset:9216
	s_waitcnt vmcnt(5)
	ds_write_b128 v181, v[10:13] offset:4096
	s_waitcnt vmcnt(4)
	ds_write_b128 v182, v[14:17] offset:13824
	s_waitcnt vmcnt(3)
	ds_write_b128 v181, v[18:21] offset:18432
	s_waitcnt vmcnt(2)
	ds_write_b128 v182, v[22:25] offset:27648
	s_waitcnt vmcnt(1)
	ds_write_b128 v181, v[26:29] offset:22528
	s_waitcnt vmcnt(0)
	ds_write_b128 v182, v[48:51] offset:32256
	v_lshl_add_u64 v[176:177], v[174:175], 0, s[0:1]
	v_bitop3_b32 v2, v86, v0, 3 bitop3:0x6c
	v_bitop3_b32 v0, v87, v0, 4 bitop3:0x36
	s_or_b32 s0, s30, s38
	v_lshlrev_b32_e32 v184, 2, v87
	v_lshlrev_b32_e32 v188, 4, v0
	v_add_u32_e32 v0, s0, v84
	v_sub_u32_e32 v0, v0, v184
	v_subrev_u32_e32 v189, s58, v0
	v_add_u32_e32 v0, s58, v184
	v_sub_u32_e32 v0, v0, v84
	v_and_b32_e32 v31, 15, v85
	v_lshlrev_b32_e32 v187, 4, v2
	v_subrev_u32_e32 v0, s38, v0
	v_mov_b32_e32 v2, v1
	v_mov_b32_e32 v3, v1
	v_lshlrev_b32_e32 v185, 7, v31
	v_mul_u32_u24_e32 v186, 0x90, v31
	v_subrev_u32_e32 v190, s30, v0
	v_mov_b32_e32 v0, v1
	v_mov_b64_e32 v[6:7], v[2:3]
	v_mov_b64_e32 v[10:11], v[2:3]
	v_mov_b64_e32 v[14:15], v[2:3]
	v_mov_b64_e32 v[18:19], v[2:3]
	v_mov_b64_e32 v[26:27], v[2:3]
	v_mov_b64_e32 v[30:31], v[2:3]
	v_mov_b64_e32 v[50:51], v[2:3]
	v_mov_b64_e32 v[86:87], v[2:3]
	v_mov_b64_e32 v[90:91], v[2:3]
	v_mov_b64_e32 v[22:23], v[2:3]
	s_mov_b32 s65, 0
	s_add_i32 s66, s35, 0xffffff80
	s_add_i32 s67, s35, 0xffffff9f
	v_mov_b64_e32 v[4:5], v[0:1]
	v_mov_b64_e32 v[8:9], v[0:1]
	v_mov_b64_e32 v[12:13], v[0:1]
	v_mov_b64_e32 v[16:17], v[0:1]
	v_mov_b64_e32 v[24:25], v[0:1]
	v_mov_b64_e32 v[28:29], v[0:1]
	v_mov_b64_e32 v[48:49], v[0:1]
	v_mov_b64_e32 v[84:85], v[0:1]
	v_mov_b64_e32 v[88:89], v[0:1]
	v_mov_b64_e32 v[20:21], v[0:1]
	s_mov_b32 s68, 0
	s_movk_i32 s74, 0x3fff
	s_movk_i32 s75, 0x210
	s_movk_i32 s76, 0xff7f
	s_mov_b32 s77, 0x40000
	s_mov_b32 s78, 0x60000
	s_waitcnt lgkmcnt(0)
	s_barrier
	v_mul_f32_e32 v219, 0x40b17218, v183
	v_mul_f32_e32 v220, 2.0, v219
	v_mul_f32_e32 v221, 0x40400000, v219
	v_mov_b32_e32 v218, 0

; __device__ __forceinline__ float fexp2(float x) { return __builtin_amdgcn_exp2f(x); }
; template <bool MASKED>
; __device__ __forceinline__ void sm_step(f32x4 (&S)[4], float c1, float slope2, float tb, int kbase, int tqn,
;                                         int window, bool selok, bf16x8 (&pb)[2]) {
; #pragma unroll
;   for (int mt = 0; mt < 4; ++mt)
; #pragma unroll
;     for (int r = 0; r < 4; ++r) {
;       float u = fmaf(slope2, (float)(mt * 16 + r), fmaf(S[mt][r], c1, tb));
;       if (MASKED) {
;         int dist = tqn - (kbase + mt * 16 + r);
;         bool valid = (dist >= 0) && (dist < window) && selok;
;         u = valid ? u : -1e30f;
;       }
;       S[mt][r] = fexp2(u);
;     }
;     ...
;     if (k0 <= qhi && (qlo - (k0 + 63)) < window) {
;       bool full = (k0 + 63 <= qlo) && (qhi - k0 < window);
;       const bool rowfull = SEL && full;
;       bool selok[NQ];
; #pragma unroll
;       for (int n = 0; n < NQ; ++n) selok[n] = true;
;       if (SEL) {
;         bool all = true;
; #pragma unroll
;         for (int n = 0; n < NQ; ++n) { selok[n] = ((selq[n] >> kt) & 1u) != 0; all = all && selok[n]; }
;         full = full && __all(all);
;       }
;       const int kbase = k0 + quad * 4;
; #pragma unroll
;       for (int mp = 0; mp < NMAP; ++mp) {
; #pragma unroll
;         for (int n = 0; n < NQ; ++n) {
;           f32x4 S[4];
; #pragma unroll
;           for (int mt = 0; mt < 4; ++mt) S[mt] = f32x4{0.f, 0.f, 0.f, 0.f};
; #pragma unroll
;           for (int ks = 0; ks < 2; ++ks) {
;             if (NMAP == 2 && ks != mp) continue;
; #pragma unroll
;             for (int mt = 0; mt < 4; ++mt) {
;               bf16x8 a = *(const bf16x8*)(cK + (mt * 16 + l15) * 64 + (((ks * 4 + quad) ^ ((l15 >> 1) & 7)) * 8));
;               S[mt] = mfma16(a, qf[n][ks], S[mt]);
;             }
;           }
;           bf16x8 pb[2];
;           const float tb = slope2 * (float)(kbase - tq[n]);
;           if (full || rowfull) {
;             sm_step<false>(S, c1, slope2, tb, kbase, tq[n], window, true, pb);
;             if (SEL && !full && !selok[n]) {
;               pb[0] = bf16x8{0, 0, 0, 0, 0, 0, 0, 0}; pb[1] = bf16x8{0, 0, 0, 0, 0, 0, 0, 0};
;             }
;           } else sm_step<true>(S, c1, slope2, tb, kbase, tq[n], window, selok[n], pb);
.LBB0_256:
	s_add_i32 s73, s58, s65
	s_cmp_gt_i32 s73, s59
	s_mul_i32 s72, s68, 0x9000
	s_cbranch_scc1 .LBB0_267
	s_add_i32 s0, s73, 63
	s_cmp_le_i32 s0, s66
	s_cbranch_scc1 .LBB0_267
	v_add_u32_e32 v0, s72, v185
	v_add_u32_e32 v2, v0, v187
	ds_read_b128 v[104:107], v2
	ds_read_b128 v[100:103], v2 offset:6144
	v_add_u32_e32 v0, v0, v188
	ds_read_b128 v[108:111], v0
	ds_read_b128 v[120:123], v0 offset:4096
	ds_read_b128 v[92:95], v2 offset:2048
	ds_read_b128 v[96:99], v2 offset:4096
	v_add_u32_e32 v198, s65, v190
	s_cmp_le_i32 s73, s67
	s_waitcnt lgkmcnt(5)
	v_mfma_f32_16x16x32_bf16 v[112:115], v[104:107], v[32:35], v[218:221]
	s_cselect_b64 s[30:31], -1, 0
	s_cmp_gt_i32 s0, s35
	s_cselect_b64 s[0:1], -1, 0
	s_waitcnt lgkmcnt(3)
	v_mfma_f32_16x16x32_bf16 v[132:135], v[108:111], v[36:39], v[112:115]
	s_or_b64 s[62:63], s[0:1], s[30:31]
	v_add_u32_e32 v197, -2, v189
	v_add_u32_e32 v196, -3, v189
	ds_read_b128 v[112:115], v0 offset:2048
	s_waitcnt lgkmcnt(2)
	v_mfma_f32_16x16x32_bf16 v[116:119], v[92:95], v[32:35], v[218:221]
	v_add_u32_e32 v195, -16, v189
	v_subrev_u32_e32 v194, 17, v189
	v_subrev_u32_e32 v193, 18, v189
	s_waitcnt lgkmcnt(0)
	v_mfma_f32_16x16x32_bf16 v[136:139], v[112:115], v[36:39], v[116:119]
	s_nop 2
	ds_read_b128 v[116:119], v0 offset:6144
	v_cvt_f32_i32_e32 v0, v198
	v_subrev_u32_e32 v192, 19, v189
	v_mfma_f32_16x16x32_bf16 v[124:127], v[96:99], v[32:35], v[218:221]
	v_subrev_u32_e32 v191, 32, v189
	v_subrev_u32_e32 v155, 33, v189
	v_subrev_u32_e32 v154, 34, v189
	v_mfma_f32_16x16x32_bf16 v[128:131], v[100:103], v[32:35], v[218:221]
	s_mov_b64 s[30:31], -1
	s_and_b64 vcc, exec, s[62:63]
	v_cmp_gt_u32_e64 s[0:1], s11, v189
	v_mfma_f32_16x16x32_bf16 v[140:143], v[120:123], v[36:39], v[124:127]
	v_cmp_gt_u32_e64 s[38:39], s11, v197
	v_cmp_gt_u32_e64 s[40:41], s11, v196
	v_cmp_gt_u32_e64 s[42:43], s11, v195
	s_waitcnt lgkmcnt(0)
	v_mfma_f32_16x16x32_bf16 v[144:147], v[116:119], v[36:39], v[128:131]
	v_mul_f32_e32 v124, v183, v0
	v_fmamk_f32 v125, v132, 0x3e38aa3b, v124
	v_fmamk_f32 v2, v133, 0x3e38aa3b, v124
	v_fmamk_f32 v126, v134, 0x3e38aa3b, v124
	v_fmamk_f32 v127, v135, 0x3e38aa3b, v124
	v_fmac_f32_e32 v124, 0x41800000, v183
	v_fmamk_f32 v128, v136, 0x3e38aa3b, v124
	v_fmamk_f32 v129, v137, 0x3e38aa3b, v124
	v_fmamk_f32 v130, v138, 0x3e38aa3b, v124
	v_fmamk_f32 v132, v139, 0x3e38aa3b, v124
	v_fmac_f32_e32 v124, 0x41800000, v183
	v_fmamk_f32 v134, v140, 0x3e38aa3b, v124
	v_fmamk_f32 v136, v141, 0x3e38aa3b, v124
	v_subrev_u32_e32 v0, 35, v189
	v_fmamk_f32 v133, v142, 0x3e38aa3b, v124
	v_fmamk_f32 v135, v143, 0x3e38aa3b, v124
	v_fmac_f32_e32 v124, 0x41800000, v183
	v_fmamk_f32 v137, v144, 0x3e38aa3b, v124
	v_fmamk_f32 v138, v145, 0x3e38aa3b, v124
	v_fmamk_f32 v131, v146, 0x3e38aa3b, v124
	v_fmac_f32_e32 v124, 0x3e38aa3b, v147
	v_mov_b32_e32 v139, v2
	v_cmp_gt_u32_e64 s[44:45], s11, v194
	v_cmp_gt_u32_e64 s[46:47], s11, v193
	v_cmp_gt_u32_e64 s[48:49], s11, v192
	v_cmp_gt_u32_e64 s[52:53], s11, v191
	v_cmp_gt_u32_e64 s[56:57], s11, v155
	v_cmp_gt_u32_e64 s[50:51], s11, v154
	v_cmp_gt_u32_e64 s[54:55], s11, v0
	s_cbranch_vccz .LBB0_260
	v_cndmask_b32_e64 v144, v226, v133, s[50:51]
	v_exp_f32_e32 v148, v144
	v_cndmask_b32_e64 v144, v226, v135, s[54:55]
	v_cndmask_b32_e64 v2, v226, v125, s[0:1]
	v_cmp_lt_u32_e32 vcc, s76, v198
	v_exp_f32_e32 v149, v144
	v_subrev_u32_e32 v144, 48, v189
	v_exp_f32_e32 v140, v2
	v_cndmask_b32_e32 v2, v226, v139, vcc
	v_cmp_gt_u32_e32 vcc, s11, v144
	v_exp_f32_e32 v141, v2
	v_cndmask_b32_e64 v2, v226, v126, s[38:39]
	v_cndmask_b32_e32 v144, v226, v137, vcc
	v_exp_f32_e32 v142, v2
	v_cndmask_b32_e64 v2, v226, v127, s[40:41]
	v_exp_f32_e32 v150, v144
	v_subrev_u32_e32 v144, 49, v189
	v_exp_f32_e32 v143, v2
	v_cndmask_b32_e64 v2, v226, v128, s[42:43]
	v_cmp_gt_u32_e32 vcc, s11, v144
	v_exp_f32_e32 v146, v2
	v_cndmask_b32_e64 v2, v226, v129, s[44:45]
	v_cndmask_b32_e32 v144, v226, v138, vcc
	v_exp_f32_e32 v147, v2
	v_cndmask_b32_e64 v2, v226, v130, s[46:47]
	v_exp_f32_e32 v151, v144
	v_subrev_u32_e32 v144, 50, v189
	v_exp_f32_e32 v199, v2
	v_cndmask_b32_e64 v2, v226, v132, s[48:49]
	v_cmp_gt_u32_e32 vcc, s11, v144
	v_exp_f32_e32 v200, v2
	v_cndmask_b32_e64 v2, v226, v134, s[52:53]
	v_cndmask_b32_e32 v144, v226, v131, vcc
	v_exp_f32_e32 v152, v144
	v_subrev_u32_e32 v144, 51, v189
	v_cmp_gt_u32_e32 vcc, s11, v144
	v_cndmask_b32_e64 v3, v226, v136, s[56:57]
	v_exp_f32_e32 v2, v2
	v_cndmask_b32_e32 v144, v226, v124, vcc
	v_exp_f32_e32 v3, v3
	v_exp_f32_e32 v153, v144
	v_cvt_pk_bf16_f32 v144, v140, v141
	v_cvt_pk_bf16_f32 v145, v142, v143
	v_cvt_pk_bf16_f32 v146, v146, v147
	v_cvt_pk_bf16_f32 v147, v199, v200
	s_mov_b64 s[30:31], 0

;     ...
;         for (int n = 0; n < NQ; ++n) {
;           f32x4 S[4];
; #pragma unroll
;           for (int mt = 0; mt < 4; ++mt) S[mt] = f32x4{0.f, 0.f, 0.f, 0.f};
; #pragma unroll
;           for (int ks = 0; ks < 2; ++ks) {
;             if (NMAP == 2 && ks != mp) continue;
; #pragma unroll
;             for (int mt = 0; mt < 4; ++mt) {
;               bf16x8 a = *(const bf16x8*)(cK + (mt * 16 + l15) * 64 + (((ks * 4 + quad) ^ ((l15 >> 1) & 7)) * 8));
;               S[mt] = mfma16(a, qf[n][ks], S[mt]);
;             }
;           }
;           bf16x8 pb[2];
;           const float tb = slope2 * (float)(kbase - tq[n]);
;           if (full || rowfull) {
;             sm_step<false>(S, c1, slope2, tb, kbase, tq[n], window, true, pb);
;             if (SEL && !full && !selok[n]) {
;               pb[0] = bf16x8{0, 0, 0, 0, 0, 0, 0, 0}; pb[1] = bf16x8{0, 0, 0, 0, 0, 0, 0, 0};
;             }
;           } else sm_step<true>(S, c1, slope2, tb, kbase, tq[n], window, selok[n], pb);
; #pragma unroll
;           for (int k2 = 0; k2 < 2; ++k2) {
; #pragma unroll
;             for (int dt = 0; dt < 4; ++dt) {
;               bf16x8 a = vt_frag(cV, dt, k2, l15, quad);
;               O[mp * NQ + n][dt] = mfma16(a, pb[k2], O[mp * NQ + n][dt]);
;             }
;             L[mp * NQ + n] = mfma16(ones, pb[k2], L[mp * NQ + n]);
;           }
.LBB0_262:
	v_lshlrev_b32_e32 v124, 1, v184
	v_add3_u32 v136, s72, v124, v186
	v_add_u32_e32 v137, 0x2000, v136
	v_add_u32_e32 v199, 0x2800, v136
	v_add_u32_e32 v208, 0x3000, v136
	v_add_u32_e32 v209, 0x3800, v136
	ds_read2_b64 v[124:127], v137 offset0:128 offset1:132
	ds_read2_b64 v[128:131], v199 offset0:160 offset1:164
	ds_read2_b64 v[132:135], v208 offset0:192 offset1:196
	ds_read2_b64 v[140:143], v209 offset0:224 offset1:228
	s_mov_b32 s30, s28
	s_mov_b32 s31, s28
	s_mov_b32 s29, s28
	v_mov_b64_e32 v[202:203], s[30:31]
	v_mov_b64_e32 v[200:201], s[28:29]
	v_cvt_pk_bf16_f32 v205, v148, v149
	v_cvt_pk_bf16_f32 v206, v150, v151
	v_mfma_f32_16x16x32_bf16 v[148:151], v[104:107], v[40:43], v[218:221]
	v_cvt_pk_bf16_f32 v207, v152, v153
	v_add_u32_e32 v153, -16, v198
	v_cvt_pk_bf16_f32 v204, v2, v3
	v_cvt_f32_i32_e32 v2, v153
	v_mfma_f32_16x16x32_bf16 v[230:233], v[108:111], v[44:47], v[148:151]
	ds_read2_b64 v[136:139], v137 offset0:136 offset1:140
	ds_read2_b64 v[104:107], v208 offset0:200 offset1:204
	ds_read2_b64 v[108:111], v209 offset0:232 offset1:236
	v_mfma_f32_16x16x32_bf16 v[92:95], v[92:95], v[40:43], v[218:221]
	v_mul_f32_e32 v148, v183, v2
	s_nop 2
	v_fmamk_f32 v149, v230, 0x3e38aa3b, v148
	v_fmamk_f32 v2, v231, 0x3e38aa3b, v148
	s_waitcnt lgkmcnt(6)
	v_mfma_f32_16x16x32_bf16 v[84:87], v[124:127], v[144:147], v[84:87]
	s_mov_b64 s[0:1], -1
	s_andn2_b64 vcc, exec, s[62:63]
	s_waitcnt lgkmcnt(5)
	v_mfma_f32_16x16x32_bf16 v[48:51], v[128:131], v[144:147], v[48:51]
	s_waitcnt lgkmcnt(4)
	v_mfma_f32_16x16x32_bf16 v[28:31], v[132:135], v[144:147], v[28:31]
	s_waitcnt lgkmcnt(3)
	v_mfma_f32_16x16x32_bf16 v[24:27], v[140:143], v[144:147], v[24:27]
	v_mfma_f32_16x16x32_bf16 v[88:91], v[200:203], v[144:147], v[88:91]
	ds_read2_b64 v[144:147], v199 offset0:168 offset1:172
	v_mfma_f32_16x16x32_bf16 v[96:99], v[96:99], v[40:43], v[218:221]
	v_mfma_f32_16x16x32_bf16 v[92:95], v[112:115], v[44:47], v[92:95]
	v_fmamk_f32 v112, v232, 0x3e38aa3b, v148
	v_fmamk_f32 v113, v233, 0x3e38aa3b, v148
	v_fmac_f32_e32 v148, 0x41800000, v183
	v_mfma_f32_16x16x32_bf16 v[230:233], v[100:103], v[40:43], v[218:221]
	s_nop 2
	s_nop 0
	v_fmamk_f32 v114, v92, 0x3e38aa3b, v148
	v_fmamk_f32 v150, v93, 0x3e38aa3b, v148
	v_fmamk_f32 v151, v94, 0x3e38aa3b, v148
	v_fmamk_f32 v152, v95, 0x3e38aa3b, v148
	v_mfma_f32_16x16x32_bf16 v[92:95], v[120:123], v[44:47], v[96:99]
	v_fmac_f32_e32 v148, 0x41800000, v183
	v_mfma_f32_16x16x32_bf16 v[96:99], v[116:119], v[44:47], v[230:233]
	s_nop 2
	s_nop 2
	v_fmamk_f32 v120, v92, 0x3e38aa3b, v148
	v_fmamk_f32 v121, v93, 0x3e38aa3b, v148
	s_waitcnt lgkmcnt(3)
	v_mfma_f32_16x16x32_bf16 v[84:87], v[136:139], v[204:207], v[84:87]
	v_fmamk_f32 v103, v94, 0x3e38aa3b, v148
	v_fmamk_f32 v115, v95, 0x3e38aa3b, v148
	v_fmac_f32_e32 v148, 0x41800000, v183
	s_waitcnt lgkmcnt(0)
	v_mfma_f32_16x16x32_bf16 v[48:51], v[144:147], v[204:207], v[48:51]
	v_fmamk_f32 v116, v96, 0x3e38aa3b, v148
	v_fmamk_f32 v117, v97, 0x3e38aa3b, v148
	v_fmamk_f32 v102, v98, 0x3e38aa3b, v148
	v_mfma_f32_16x16x32_bf16 v[28:31], v[104:107], v[204:207], v[28:31]
	v_fmac_f32_e32 v148, 0x3e38aa3b, v99
	v_mov_b32_e32 v118, v2
	v_mfma_f32_16x16x32_bf16 v[24:27], v[108:111], v[204:207], v[24:27]
	v_mfma_f32_16x16x32_bf16 v[88:91], v[200:203], v[204:207], v[88:91]
	s_cbranch_vccnz .LBB0_264
	v_add_u32_e32 v2, 16, v189
	v_cmp_gt_u32_e32 vcc, s11, v2
	s_mov_b64 s[0:1], 0
	s_nop 0
	v_cndmask_b32_e32 v2, v226, v149, vcc
	v_cmp_lt_u32_e32 vcc, s76, v153
	v_exp_f32_e32 v92, v2
	s_nop 0
	v_cndmask_b32_e32 v2, v226, v118, vcc
	v_exp_f32_e32 v93, v2
	v_add_u32_e32 v2, 14, v189
	v_cmp_gt_u32_e32 vcc, s11, v2
	v_cvt_pk_bf16_f32 v92, v92, v93
	s_nop 0
	v_cndmask_b32_e32 v2, v226, v112, vcc
	v_exp_f32_e32 v94, v2
	v_add_u32_e32 v2, 13, v189
	v_cmp_gt_u32_e32 vcc, s11, v2
	s_nop 1
	v_cndmask_b32_e32 v2, v226, v113, vcc
	v_cmp_gt_u32_e32 vcc, s11, v189
	v_exp_f32_e32 v95, v2
	s_nop 0
	v_cndmask_b32_e32 v2, v226, v114, vcc
	v_exp_f32_e32 v119, v2
	v_add_u32_e32 v2, -1, v189
	v_cmp_gt_u32_e32 vcc, s11, v2
	v_cvt_pk_bf16_f32 v93, v94, v95
	s_nop 0
	v_cndmask_b32_e32 v2, v226, v150, vcc
	v_cmp_gt_u32_e32 vcc, s11, v197
	v_exp_f32_e32 v122, v2
	s_nop 0
	v_cndmask_b32_e32 v2, v226, v151, vcc
	v_cmp_gt_u32_e32 vcc, s11, v196
	v_exp_f32_e32 v123, v2
	v_cvt_pk_bf16_f32 v94, v119, v122
	v_cndmask_b32_e32 v2, v226, v152, vcc
	v_cmp_gt_u32_e32 vcc, s11, v195
	v_exp_f32_e32 v153, v2
	s_nop 0
	v_cndmask_b32_e32 v2, v226, v120, vcc
	v_cmp_gt_u32_e32 vcc, s11, v194
	v_exp_f32_e32 v2, v2
	v_cvt_pk_bf16_f32 v95, v123, v153
	v_cndmask_b32_e32 v3, v226, v121, vcc
	v_cmp_gt_u32_e32 vcc, s11, v193
	v_exp_f32_e32 v3, v3
	s_nop 0
	v_cndmask_b32_e32 v96, v226, v103, vcc
	v_cmp_gt_u32_e32 vcc, s11, v192
	v_exp_f32_e32 v96, v96
	s_nop 0
	v_cndmask_b32_e32 v97, v226, v115, vcc
	v_cmp_gt_u32_e32 vcc, s11, v191
	v_exp_f32_e32 v97, v97
	s_nop 0
	v_cndmask_b32_e32 v98, v226, v116, vcc
	v_cmp_gt_u32_e32 vcc, s11, v155
	v_exp_f32_e32 v98, v98
	s_nop 0
	v_cndmask_b32_e32 v99, v226, v117, vcc
	v_cmp_gt_u32_e32 vcc, s11, v154
	v_exp_f32_e32 v99, v99
	s_nop 0
	v_cndmask_b32_e32 v100, v226, v102, vcc
	v_cmp_gt_u32_e32 vcc, s11, v0
	v_exp_f32_e32 v100, v100
	s_nop 0
	v_cndmask_b32_e32 v0, v226, v148, vcc
	v_exp_f32_e32 v101, v0

; __device__ __forceinline__ float fexp2(float x) { return __builtin_amdgcn_exp2f(x); }
; template <bool MASKED>
; __device__ __forceinline__ void sm_step(f32x4 (&S)[4], float c1, float slope2, float tb, int kbase, int tqn,
;                                         int window, bool selok, bf16x8 (&pb)[2]) {
; #pragma unroll
;   for (int mt = 0; mt < 4; ++mt)
; #pragma unroll
;     for (int r = 0; r < 4; ++r) {
;       float u = fmaf(slope2, (float)(mt * 16 + r), fmaf(S[mt][r], c1, tb));
;       if (MASKED) {
;         int dist = tqn - (kbase + mt * 16 + r);
;         bool valid = (dist >= 0) && (dist < window) && selok;
;         u = valid ? u : -1e30f;
;       }
;       S[mt][r] = fexp2(u);
;     }
;     ...
;     if (k0 <= qhi && (qlo - (k0 + 63)) < window) {
;       bool full = (k0 + 63 <= qlo) && (qhi - k0 < window);
;       const bool rowfull = SEL && full;
;       bool selok[NQ];
; #pragma unroll
;       for (int n = 0; n < NQ; ++n) selok[n] = true;
;       if (SEL) {
;         bool all = true;
; #pragma unroll
;         for (int n = 0; n < NQ; ++n) { selok[n] = ((selq[n] >> kt) & 1u) != 0; all = all && selok[n]; }
;         full = full && __all(all);
;       }
;       const int kbase = k0 + quad * 4;
; #pragma unroll
;       for (int mp = 0; mp < NMAP; ++mp) {
; #pragma unroll
;         for (int n = 0; n < NQ; ++n) {
;           f32x4 S[4];
; #pragma unroll
;           for (int mt = 0; mt < 4; ++mt) S[mt] = f32x4{0.f, 0.f, 0.f, 0.f};
; #pragma unroll
;           for (int ks = 0; ks < 2; ++ks) {
;             if (NMAP == 2 && ks != mp) continue;
; #pragma unroll
;             for (int mt = 0; mt < 4; ++mt) {
;               bf16x8 a = *(const bf16x8*)(cK + (mt * 16 + l15) * 64 + (((ks * 4 + quad) ^ ((l15 >> 1) & 7)) * 8));
;               S[mt] = mfma16(a, qf[n][ks], S[mt]);
;             }
;           }
;           bf16x8 pb[2];
;           const float tb = slope2 * (float)(kbase - tq[n]);
;           if (full || rowfull) {
;             sm_step<false>(S, c1, slope2, tb, kbase, tq[n], window, true, pb);
;             if (SEL && !full && !selok[n]) {
;               pb[0] = bf16x8{0, 0, 0, 0, 0, 0, 0, 0}; pb[1] = bf16x8{0, 0, 0, 0, 0, 0, 0, 0};
;             }
;           } else sm_step<true>(S, c1, slope2, tb, kbase, tq[n], window, selok[n], pb);
.LBB0_267:
	s_add_i32 s0, s73, 64
	s_cmp_gt_u32 s0, s59
	s_cbranch_scc1 .LBB0_278
	s_addk_i32 s73, 0x7f
	s_cmp_le_i32 s73, s66
	s_cbranch_scc1 .LBB0_278
	v_add_u32_e32 v0, s72, v185
	v_add_u32_e32 v2, v0, v187
	ds_read_b128 v[92:95], v2 offset:18432
	ds_read_b128 v[96:99], v2 offset:20480
	ds_read_b128 v[100:103], v2 offset:22528
	ds_read_b128 v[104:107], v2 offset:24576
	v_add_u32_e32 v0, v0, v188
	ds_read_b128 v[108:111], v0 offset:18432
	ds_read_b128 v[116:119], v0 offset:20480
	ds_read_b128 v[124:127], v0 offset:22528
	ds_read_b128 v[132:135], v0 offset:24576
	s_waitcnt lgkmcnt(7)
	v_mfma_f32_16x16x32_bf16 v[112:115], v[92:95], v[32:35], v[218:221]
	v_add_u32_e32 v201, s65, v190
	v_add_u32_e32 v140, 64, v201
	v_cvt_f32_i32_e32 v0, v140
	s_waitcnt lgkmcnt(6)
	v_mfma_f32_16x16x32_bf16 v[120:123], v[96:99], v[32:35], v[218:221]
	s_cmp_gt_i32 s0, s67
	s_cselect_b64 s[0:1], -1, 0
	s_cmp_le_u32 s73, s35
	s_waitcnt lgkmcnt(5)
	v_mfma_f32_16x16x32_bf16 v[128:131], v[100:103], v[32:35], v[218:221]
	s_cselect_b64 s[30:31], -1, 0
	s_and_b64 s[30:31], s[30:31], s[0:1]
	v_subrev_u32_e32 v200, 64, v189
	s_waitcnt lgkmcnt(4)
	v_mfma_f32_16x16x32_bf16 v[136:139], v[104:107], v[32:35], v[218:221]
	v_add_u32_e32 v199, 0xffffffbe, v189
	v_add_u32_e32 v198, 0xffffffbd, v189
	v_add_u32_e32 v197, 0xffffffb0, v189
	s_waitcnt lgkmcnt(3)
	v_mfma_f32_16x16x32_bf16 v[112:115], v[108:111], v[36:39], v[112:115]
	v_add_u32_e32 v196, 0xffffffaf, v189
	v_add_u32_e32 v195, 0xffffffae, v189
	v_add_u32_e32 v194, 0xffffffad, v189
	s_waitcnt lgkmcnt(2)
	v_mfma_f32_16x16x32_bf16 v[142:145], v[116:119], v[36:39], v[120:123]
	v_add_u32_e32 v193, 0xffffffa0, v189
	v_add_u32_e32 v192, 0xffffff9f, v189
	v_add_u32_e32 v191, 0xffffff9e, v189
	s_waitcnt lgkmcnt(1)
	v_mfma_f32_16x16x32_bf16 v[146:149], v[124:127], v[36:39], v[128:131]
	v_mul_f32_e32 v122, v183, v0
	v_fmamk_f32 v123, v112, 0x3e38aa3b, v122
	v_fmamk_f32 v2, v113, 0x3e38aa3b, v122
	s_waitcnt lgkmcnt(0)
	v_mfma_f32_16x16x32_bf16 v[150:153], v[132:135], v[36:39], v[136:139]
	v_fmamk_f32 v128, v114, 0x3e38aa3b, v122
	v_fmamk_f32 v129, v115, 0x3e38aa3b, v122
	v_fmac_f32_e32 v122, 0x41800000, v183
	v_fmamk_f32 v130, v142, 0x3e38aa3b, v122
	v_fmamk_f32 v131, v143, 0x3e38aa3b, v122
	v_fmamk_f32 v136, v144, 0x3e38aa3b, v122
	v_fmamk_f32 v138, v145, 0x3e38aa3b, v122
	v_fmac_f32_e32 v122, 0x41800000, v183
	v_fmamk_f32 v144, v146, 0x3e38aa3b, v122
	v_fmamk_f32 v146, v147, 0x3e38aa3b, v122
	v_add_u32_e32 v0, 0xffffff9d, v189
	v_fmamk_f32 v139, v148, 0x3e38aa3b, v122
	v_fmamk_f32 v145, v149, 0x3e38aa3b, v122
	v_fmac_f32_e32 v122, 0x41800000, v183
	v_fmamk_f32 v147, v150, 0x3e38aa3b, v122
	s_mov_b64 s[62:63], -1
	v_fmamk_f32 v148, v151, 0x3e38aa3b, v122
	s_and_b64 vcc, exec, s[30:31]
	v_cmp_gt_u32_e64 s[38:39], s11, v200
	v_fmamk_f32 v137, v152, 0x3e38aa3b, v122
	v_fmac_f32_e32 v122, 0x3e38aa3b, v153
	v_cmp_gt_u32_e64 s[0:1], s11, v199
	v_mov_b32_e32 v149, v2
	v_cmp_gt_u32_e64 s[40:41], s11, v198
	v_cmp_gt_u32_e64 s[42:43], s11, v197
	v_cmp_gt_u32_e64 s[44:45], s11, v196
	v_cmp_gt_u32_e64 s[46:47], s11, v195
	v_cmp_gt_u32_e64 s[48:49], s11, v194
	v_cmp_gt_u32_e64 s[52:53], s11, v193
	v_cmp_gt_u32_e64 s[56:57], s11, v192
	v_cmp_gt_u32_e64 s[50:51], s11, v191
	v_cmp_gt_u32_e64 s[54:55], s11, v0
	s_cbranch_vccnz .LBB0_271
	v_cndmask_b32_e64 v2, v226, v123, s[38:39]
	v_cmp_lt_u32_e32 vcc, s76, v140
	v_exp_f32_e32 v141, v2
	v_add_u32_e32 v114, 0xffffff90, v189
	v_cndmask_b32_e32 v2, v226, v149, vcc
	v_exp_f32_e32 v140, v2
	v_cndmask_b32_e64 v2, v226, v128, s[0:1]
	v_exp_f32_e32 v142, v2
	v_cndmask_b32_e64 v2, v226, v129, s[40:41]
	v_exp_f32_e32 v143, v2
	v_cndmask_b32_e64 v2, v226, v130, s[42:43]
	v_cmp_gt_u32_e32 vcc, s11, v114
	v_add_u32_e32 v115, 0xffffff8f, v189
	v_exp_f32_e32 v150, v2
	v_cndmask_b32_e64 v2, v226, v131, s[44:45]
	v_cndmask_b32_e32 v114, v226, v147, vcc
	v_cmp_gt_u32_e32 vcc, s11, v115
	v_add_u32_e32 v120, 0xffffff8e, v189
	v_exp_f32_e32 v151, v2
	v_cndmask_b32_e64 v2, v226, v136, s[46:47]
	v_cndmask_b32_e32 v115, v226, v148, vcc
	v_cmp_gt_u32_e32 vcc, s11, v120
	v_add_u32_e32 v121, 0xffffff8d, v189
	v_exp_f32_e32 v152, v2
	v_cndmask_b32_e64 v2, v226, v138, s[48:49]
	v_cndmask_b32_e32 v120, v226, v137, vcc
	v_cmp_gt_u32_e32 vcc, s11, v121
	v_exp_f32_e32 v153, v2
	v_cndmask_b32_e64 v2, v226, v144, s[52:53]
	v_cndmask_b32_e64 v3, v226, v146, s[56:57]
	v_cndmask_b32_e64 v112, v226, v139, s[50:51]
	v_cndmask_b32_e64 v113, v226, v145, s[54:55]
	v_cndmask_b32_e32 v121, v226, v122, vcc
	v_exp_f32_e32 v2, v2
	v_exp_f32_e32 v3, v3
	v_exp_f32_e32 v112, v112
	v_exp_f32_e32 v113, v113
	v_exp_f32_e32 v114, v114
	v_exp_f32_e32 v115, v115
	v_exp_f32_e32 v120, v120
	v_exp_f32_e32 v121, v121
	v_cvt_pk_bf16_f32 v140, v141, v140
	v_cvt_pk_bf16_f32 v141, v142, v143
	v_cvt_pk_bf16_f32 v142, v150, v151
	v_cvt_pk_bf16_f32 v143, v152, v153
	s_mov_b64 s[62:63], 0

;     ...
;         for (int n = 0; n < NQ; ++n) {
;           f32x4 S[4];
; #pragma unroll
;           for (int mt = 0; mt < 4; ++mt) S[mt] = f32x4{0.f, 0.f, 0.f, 0.f};
; #pragma unroll
;           for (int ks = 0; ks < 2; ++ks) {
;             if (NMAP == 2 && ks != mp) continue;
; #pragma unroll
;             for (int mt = 0; mt < 4; ++mt) {
;               bf16x8 a = *(const bf16x8*)(cK + (mt * 16 + l15) * 64 + (((ks * 4 + quad) ^ ((l15 >> 1) & 7)) * 8));
;               S[mt] = mfma16(a, qf[n][ks], S[mt]);
;             }
;           }
;           bf16x8 pb[2];
;           const float tb = slope2 * (float)(kbase - tq[n]);
;           if (full || rowfull) {
;             sm_step<false>(S, c1, slope2, tb, kbase, tq[n], window, true, pb);
;             if (SEL && !full && !selok[n]) {
;               pb[0] = bf16x8{0, 0, 0, 0, 0, 0, 0, 0}; pb[1] = bf16x8{0, 0, 0, 0, 0, 0, 0, 0};
;             }
;           } else sm_step<true>(S, c1, slope2, tb, kbase, tq[n], window, selok[n], pb);
; #pragma unroll
;           for (int k2 = 0; k2 < 2; ++k2) {
; #pragma unroll
;             for (int dt = 0; dt < 4; ++dt) {
;               bf16x8 a = vt_frag(cV, dt, k2, l15, quad);
;               O[mp * NQ + n][dt] = mfma16(a, pb[k2], O[mp * NQ + n][dt]);
;             }
;             L[mp * NQ + n] = mfma16(ones, pb[k2], L[mp * NQ + n]);
;           }
.LBB0_273:
	v_lshlrev_b32_e32 v122, 1, v184
	v_cvt_pk_bf16_f32 v202, v2, v3
	v_add3_u32 v2, s72, v122, v186
	v_add_u32_e32 v3, 0x6800, v2
	v_add_u32_e32 v144, 0x7000, v2
	v_add_u32_e32 v148, 0x7800, v2
	v_add_u32_e32 v2, 0x8000, v2
	v_cvt_pk_bf16_f32 v203, v112, v113
	v_cvt_pk_bf16_f32 v204, v114, v115
	v_cvt_pk_bf16_f32 v205, v120, v121
	ds_read2_b64 v[112:115], v3 offset0:128 offset1:132
	ds_read2_b64 v[120:123], v144 offset0:160 offset1:164
	ds_read2_b64 v[128:131], v148 offset0:192 offset1:196
	ds_read2_b64 v[136:139], v2 offset0:224 offset1:228
	s_xor_b64 s[0:1], s[30:31], -1
	s_mov_b32 s30, s28
	s_mov_b32 s31, s28
	s_mov_b32 s29, s28
	v_mov_b64_e32 v[208:209], s[30:31]
	v_mov_b64_e32 v[206:207], s[28:29]
	s_waitcnt lgkmcnt(3)
	v_mfma_f32_16x16x32_bf16 v[84:87], v[112:115], v[140:143], v[84:87]
	ds_read2_b64 v[144:147], v144 offset0:168 offset1:172
	ds_read2_b64 v[148:151], v148 offset0:200 offset1:204
	ds_read2_b64 v[152:155], v2 offset0:232 offset1:236
	s_waitcnt lgkmcnt(5)
	v_mfma_f32_16x16x32_bf16 v[48:51], v[120:123], v[140:143], v[48:51]
	s_mov_b64 s[30:31], -1
	s_andn2_b64 vcc, exec, s[0:1]
	s_waitcnt lgkmcnt(4)
	v_mfma_f32_16x16x32_bf16 v[28:31], v[128:131], v[140:143], v[28:31]
	s_waitcnt lgkmcnt(3)
	v_mfma_f32_16x16x32_bf16 v[24:27], v[136:139], v[140:143], v[24:27]
	v_mfma_f32_16x16x32_bf16 v[88:91], v[206:209], v[140:143], v[88:91]
	ds_read2_b64 v[140:143], v3 offset0:136 offset1:140
	v_mfma_f32_16x16x32_bf16 v[92:95], v[92:95], v[40:43], v[218:221]
	v_mfma_f32_16x16x32_bf16 v[96:99], v[96:99], v[40:43], v[218:221]
	v_mfma_f32_16x16x32_bf16 v[100:103], v[100:103], v[40:43], v[218:221]
	v_mfma_f32_16x16x32_bf16 v[104:107], v[104:107], v[40:43], v[218:221]
	v_mfma_f32_16x16x32_bf16 v[108:111], v[108:111], v[44:47], v[92:95]
	s_nop 3
	v_add_u32_e32 v92, 48, v201
	v_cvt_f32_i32_e32 v2, v92
	v_mfma_f32_16x16x32_bf16 v[94:97], v[116:119], v[44:47], v[96:99]
	v_mfma_f32_16x16x32_bf16 v[98:101], v[124:127], v[44:47], v[100:103]
	v_mfma_f32_16x16x32_bf16 v[124:127], v[132:135], v[44:47], v[104:107]
	s_nop 1
	v_mul_f32_e32 v102, v183, v2
	v_fmamk_f32 v103, v108, 0x3e38aa3b, v102
	v_fmamk_f32 v2, v109, 0x3e38aa3b, v102
	s_waitcnt lgkmcnt(0)
	v_mfma_f32_16x16x32_bf16 v[84:87], v[140:143], v[202:205], v[84:87]
	v_fmamk_f32 v104, v110, 0x3e38aa3b, v102
	v_fmamk_f32 v105, v111, 0x3e38aa3b, v102
	v_fmac_f32_e32 v102, 0x41800000, v183
	v_mfma_f32_16x16x32_bf16 v[48:51], v[144:147], v[202:205], v[48:51]
	v_fmamk_f32 v106, v94, 0x3e38aa3b, v102
	v_fmamk_f32 v107, v95, 0x3e38aa3b, v102
	v_fmamk_f32 v108, v96, 0x3e38aa3b, v102
	v_mfma_f32_16x16x32_bf16 v[28:31], v[148:151], v[202:205], v[28:31]
	v_fmamk_f32 v109, v97, 0x3e38aa3b, v102
	v_fmac_f32_e32 v102, 0x41800000, v183
	v_fmamk_f32 v110, v98, 0x3e38aa3b, v102
	v_mfma_f32_16x16x32_bf16 v[24:27], v[152:155], v[202:205], v[24:27]
	v_fmamk_f32 v111, v99, 0x3e38aa3b, v102
	v_fmamk_f32 v116, v100, 0x3e38aa3b, v102
	v_fmamk_f32 v117, v101, 0x3e38aa3b, v102
	v_mfma_f32_16x16x32_bf16 v[88:91], v[206:209], v[202:205], v[88:91]
	v_fmac_f32_e32 v102, 0x41800000, v183
	v_fmamk_f32 v118, v124, 0x3e38aa3b, v102
	v_fmamk_f32 v124, v125, 0x3e38aa3b, v102
	v_fmamk_f32 v119, v126, 0x3e38aa3b, v102
	v_fmac_f32_e32 v102, 0x3e38aa3b, v127
	v_mov_b32_e32 v125, v2
	s_cbranch_vccnz .LBB0_275
	v_subrev_u32_e32 v2, 48, v189
	v_cmp_gt_u32_e32 vcc, s11, v2
	s_mov_b64 s[30:31], 0
	s_nop 0
	v_cndmask_b32_e32 v2, v226, v103, vcc
	v_cmp_lt_u32_e32 vcc, s76, v92
	v_exp_f32_e32 v93, v2
	s_nop 0
	v_cndmask_b32_e32 v2, v226, v125, vcc
	v_exp_f32_e32 v92, v2
	v_subrev_u32_e32 v2, 50, v189
	v_cmp_gt_u32_e32 vcc, s11, v2
	v_cvt_pk_bf16_f32 v92, v93, v92
	s_nop 0
	v_cndmask_b32_e32 v2, v226, v104, vcc
	v_exp_f32_e32 v94, v2
	v_subrev_u32_e32 v2, 51, v189
	v_cmp_gt_u32_e32 vcc, s11, v2
	s_nop 1
	v_cndmask_b32_e32 v2, v226, v105, vcc
	v_cmp_gt_u32_e32 vcc, s11, v200
	v_exp_f32_e32 v95, v2
	s_nop 0
	v_cndmask_b32_e32 v2, v226, v106, vcc
	v_exp_f32_e32 v126, v2
	v_add_u32_e32 v2, 0xffffffbf, v189
	v_cmp_gt_u32_e32 vcc, s11, v2
	v_cvt_pk_bf16_f32 v93, v94, v95
	s_nop 0
	v_cndmask_b32_e32 v2, v226, v107, vcc
	v_cmp_gt_u32_e32 vcc, s11, v199
	v_exp_f32_e32 v127, v2
	s_nop 0
	v_cndmask_b32_e32 v2, v226, v108, vcc
	v_cmp_gt_u32_e32 vcc, s11, v198
	v_exp_f32_e32 v132, v2
	v_cvt_pk_bf16_f32 v94, v126, v127
	v_cndmask_b32_e32 v2, v226, v109, vcc
	v_cmp_gt_u32_e32 vcc, s11, v197
	v_exp_f32_e32 v133, v2
	s_nop 0
	v_cndmask_b32_e32 v2, v226, v110, vcc
	v_cmp_gt_u32_e32 vcc, s11, v196
	v_exp_f32_e32 v2, v2
	v_cvt_pk_bf16_f32 v95, v132, v133
	v_cndmask_b32_e32 v3, v226, v111, vcc
	v_cmp_gt_u32_e32 vcc, s11, v195
	v_exp_f32_e32 v3, v3
	s_nop 0
	v_cndmask_b32_e32 v96, v226, v116, vcc
	v_cmp_gt_u32_e32 vcc, s11, v194
	v_exp_f32_e32 v96, v96
	s_nop 0
	v_cndmask_b32_e32 v97, v226, v117, vcc
	v_cmp_gt_u32_e32 vcc, s11, v193
	v_exp_f32_e32 v97, v97
	s_nop 0
	v_cndmask_b32_e32 v98, v226, v118, vcc
	v_cmp_gt_u32_e32 vcc, s11, v192
	v_exp_f32_e32 v98, v98
	s_nop 0
	v_cndmask_b32_e32 v99, v226, v124, vcc
	v_cmp_gt_u32_e32 vcc, s11, v191
	v_exp_f32_e32 v99, v99
	s_nop 0
	v_cndmask_b32_e32 v100, v226, v119, vcc
	v_cmp_gt_u32_e32 vcc, s11, v0
	v_exp_f32_e32 v100, v100
	s_nop 0
	v_cndmask_b32_e32 v0, v226, v102, vcc
	v_exp_f32_e32 v101, v0

; __device__ void phase_setup(const Params& p, unsigned char* smem) {
;     ...
;     __syncthreads();
; #pragma unroll
;     for (int i = 0; i < 16; ++i) tile[(ty + 4 * i) * 65 + tx] = vals[i];
;     __syncthreads();
;     u32x4 a, b;
; #pragma unroll
;     for (int j = 0; j < 4; ++j) {
;       a[j] = pack2(tile[(kc + 2 * j) * 65 + nl], tile[(kc + 2 * j + 1) * 65 + nl]);
;       b[j] = pack2(tile[(kc + 8 + 2 * j) * 65 + nl], tile[(kc + 8 + 2 * j + 1) * 65 + nl]);
;     }
;     u16* d = cur.dst + (size_t)(cur.n0 + nl) * cur.K + cur.k0 + kc;
;     *(u32x4*)d = a;
;     *(u32x4*)(d + 8) = b;
; #pragma unroll
;     for (int i = 0; i < 16; ++i) { vals[i] = nvals[i]; nvals[i] = nvals2[i]; }
;     cur = nxt; nxt = nx2;
;     it = nit;
.LBB0_444:
	s_barrier
	s_waitcnt vmcnt(0)
	ds_write_b32 v40, v7
	ds_write_b32 v40, v6 offset:1040
	ds_write_b32 v40, v9 offset:2080
	ds_write_b32 v40, v8 offset:3120
	ds_write_b32 v40, v11 offset:4160
	ds_write_b32 v40, v10 offset:5200
	ds_write_b32 v40, v13 offset:6240
	ds_write_b32 v40, v12 offset:7280
	ds_write_b32 v40, v15 offset:8320
	ds_write_b32 v40, v14 offset:9360
	ds_write_b32 v40, v17 offset:10400
	ds_write_b32 v40, v16 offset:11440
	ds_write_b32 v40, v19 offset:12480
	ds_write_b32 v40, v18 offset:13520
	ds_write_b32 v40, v21 offset:14560
	ds_write_b32 v40, v20 offset:15600
	s_waitcnt lgkmcnt(0)
	s_barrier
	ds_read2_b32 v[2:3], v39 offset1:65
	v_add_u32_e32 v8, 0x800, v39
	v_add_u32_e32 v9, 0x400, v39
	v_add_u32_e32 v13, 0xc00, v39
	s_add_i32 s46, s46, s12
	s_waitcnt lgkmcnt(0)
	v_cvt_pk_bf16_f32 v6, v2, v3
	ds_read2_b32 v[2:3], v8 offset0:8 offset1:73
	s_add_i32 s39, s39, s42
	s_add_i32 s43, s43, s44
	s_add_i32 s45, s45, s38
	v_mov_b32_e32 v20, v37
	s_waitcnt lgkmcnt(0)
	v_cvt_pk_bf16_f32 v10, v2, v3
	ds_read2_b32 v[2:3], v39 offset0:130 offset1:195
	v_mov_b32_e32 v21, v36
	v_mov_b32_e32 v18, v35
	v_mov_b32_e32 v19, v34
	v_mov_b32_e32 v16, v33
	s_waitcnt lgkmcnt(0)
	v_cvt_pk_bf16_f32 v7, v2, v3
	ds_read2_b32 v[2:3], v8 offset0:138 offset1:203
	v_mov_b32_e32 v17, v32
	v_mov_b32_e32 v14, v31
	v_mov_b32_e32 v15, v30
	v_mov_b32_e32 v37, v55
	s_waitcnt lgkmcnt(0)
	v_cvt_pk_bf16_f32 v11, v2, v3
	ds_read2_b32 v[2:3], v9 offset0:4 offset1:69
	v_mov_b32_e32 v36, v56
	v_mov_b32_e32 v35, v53
	v_mov_b32_e32 v34, v54
	v_mov_b32_e32 v33, v51
	s_waitcnt lgkmcnt(0)
	v_cvt_pk_bf16_f32 v8, v2, v3
	ds_read2_b32 v[2:3], v13 offset0:12 offset1:77
	v_mov_b32_e32 v32, v52
	v_mov_b32_e32 v31, v49
	v_mov_b32_e32 v30, v50
	s_waitcnt lgkmcnt(0)
	v_cvt_pk_bf16_f32 v12, v2, v3
	ds_read2_b32 v[2:3], v9 offset0:134 offset1:199
	s_waitcnt lgkmcnt(0)
	v_cvt_pk_bf16_f32 v9, v2, v3
	ds_read2_b32 v[2:3], v13 offset0:142 offset1:207
	s_waitcnt lgkmcnt(0)
	v_cvt_pk_bf16_f32 v13, v2, v3
	v_add_u32_e32 v2, s1, v38
	s_cmpk_eq_i32 s29, 0x800
	s_cbranch_scc0 .Lsetup_std
	v_lshrrev_b32_e32 v3, 4, v2
	v_and_b32_e32 v2, 15, v2
	v_lshlrev_b32_e32 v2, 4, v2
	v_lshl_or_b32 v2, v3, 10, v2
	v_lshrrev_b32_e32 v3, 6, v0
	v_lshl_add_u32 v2, v3, 13, v2
	v_bfe_u32 v3, v0, 4, 2
	v_lshl_add_u32 v2, v3, 8, v2
	s_lshl_b32 s24, s0, 8
	v_add_u32_e32 v2, s24, v2
	v_mov_b32_e32 v3, 0
	s_ashr_i32 s1, s0, 31
	v_lshl_add_u64 v[2:3], s[6:7], 0, v[2:3]
	global_store_dwordx4 v[2:3], v[6:9], off
	global_store_dwordx4 v[2:3], v[10:13], off offset:256
	s_branch .Lsetup_join
.Lsetup_std:
	v_mad_i64_i32 v[2:3], s[24:25], s29, v2, 0
	v_lshl_add_u64 v[2:3], v[2:3], 1, s[6:7]
	s_ashr_i32 s1, s0, 31
	v_lshl_add_u64 v[2:3], s[0:1], 1, v[2:3]
	v_lshl_add_u64 v[2:3], v[2:3], 0, v[0:1]
	global_store_dwordx4 v[2:3], v[6:9], off
	global_store_dwordx4 v[2:3], v[10:13], off offset:16
.Lsetup_join:
	s_cmpk_lt_i32 s46, 0x1490
	v_mov_b32_e32 v8, v25
	v_mov_b32_e32 v12, v29
	v_mov_b32_e32 v13, v28
	v_mov_b32_e32 v10, v27
	v_mov_b32_e32 v11, v26
	v_mov_b32_e32 v9, v24
	v_mov_b32_e32 v6, v23
	v_mov_b32_e32 v7, v22
	v_mov_b32_e32 v29, v47
	v_mov_b32_e32 v28, v48
	v_mov_b32_e32 v27, v45
	v_mov_b32_e32 v26, v46
	v_mov_b32_e32 v25, v43
	v_mov_b32_e32 v24, v44
	v_mov_b32_e32 v23, v41
	v_mov_b32_e32 v22, v42
	s_mov_b32 s1, s40
	s_mov_b32 s0, s35
	s_mov_b32 s29, s41
	s_mov_b64 s[6:7], s[8:9]
	s_mov_b32 s40, s48
	s_mov_b32 s35, s47
	s_mov_b32 s41, s49
	s_mov_b64 s[8:9], s[18:19]
	s_cbranch_scc0 .LBB0_490
